# GEMM K-loops (4 of 10): next-tile pointer select SALU moved from the heaviest load segment to the head of the second load segment
# baseline (speedup 1.0000x reference)
; #define WAIT_V(n) asm volatile("s_waitcnt vmcnt(" #n ")" ::: "memory")
; #define WAIT_L(n) asm volatile("s_waitcnt lgkmcnt(" #n ")" ::: "memory")
; #define BAR __builtin_amdgcn_s_barrier()
; #define SCHED __builtin_amdgcn_sched_barrier(0)
; template <class Get, class Epi>
; DI void gemm_stream(LAS unsigned char* lds, const int K, const int ld, Get get, Epi epi) {
;     ...
;             const bool last = (t == nt - 2);
;             const char* a1 = cA + (size_t)(t + 1) * kstep;
;             const char* a2 = last ? nA : cA + (size_t)(t + 2) * kstep;
;             const char* b2 = last ? nB : cB + (size_t)(t + 2) * kstep;
;             const char* a3 = a2 + kstep;
;             const char* b3 = b2 + kstep;
;             LDB(B0, 0, 0); SCHED; LDA(At, 0, 0); STAGE(SAo(1, 1), a1 + hstep);
;             WAIT_L(8); BAR; WAIT_L(0); MMA(0, 0, At, B0); BAR; SCHED;
;             LDB(B1, 0, 1); STAGE(SBo(0, 0), b2);
;             BAR; WAIT_L(0); MMA(0, 1, At, B1); BAR;
;             LDA(At, 0, 1); STAGE(SAo(0, 0), a2);
;             BAR; WAIT_L(0); MMA(1, 0, At, B0); BAR; SCHED;
;             STAGE(SBo(0, 1), b2 + hstep);
;             WAIT_V(6); BAR; MMA(1, 1, At, B1); BAR;
.LBB0_1238:
	ds_read_b128 v[128:131], v198
	ds_read_b128 v[132:135], v198 offset:1024
	ds_read_b128 v[136:139], v198 offset:2048
	ds_read_b128 v[140:143], v198 offset:3072
	s_mov_b32 m0, s74
	v_lshl_add_u64 v[186:187], s[6:7], 0, v[168:169]
	ds_read_b128 v[144:147], v199
	ds_read_b128 v[148:151], v199 offset:1024
	ds_read_b128 v[152:155], v199 offset:2048
	ds_read_b128 v[156:159], v199 offset:3072
	ds_read_b128 v[160:163], v199 offset:4096
	ds_read_b128 v[174:177], v199 offset:5120
	ds_read_b128 v[178:181], v199 offset:6144
	ds_read_b128 v[182:185], v199 offset:7168
	global_load_lds_dwordx4 v[186:187], off
	v_lshl_add_u64 v[186:187], s[6:7], 0, v[170:171]
	s_mov_b32 m0, s75
	s_nop 0
	global_load_lds_dwordx4 v[186:187], off
	s_waitcnt lgkmcnt(8)
	s_barrier
	s_waitcnt lgkmcnt(0)
	v_mfma_f32_16x16x32_bf16 v[124:127], v[128:131], v[144:147], v[124:127]
	v_mfma_f32_16x16x32_bf16 v[92:95], v[136:139], v[144:147], v[92:95]
	v_mfma_f32_16x16x32_bf16 v[120:123], v[128:131], v[152:155], v[120:123]
	v_mfma_f32_16x16x32_bf16 v[88:91], v[136:139], v[152:155], v[88:91]
	v_mfma_f32_16x16x32_bf16 v[116:119], v[128:131], v[160:163], v[116:119]
	v_mfma_f32_16x16x32_bf16 v[84:87], v[136:139], v[160:163], v[84:87]
	v_mfma_f32_16x16x32_bf16 v[112:115], v[128:131], v[178:181], v[112:115]
	v_mfma_f32_16x16x32_bf16 v[80:83], v[136:139], v[178:181], v[80:83]
	v_mfma_f32_16x16x32_bf16 v[124:127], v[132:135], v[148:151], v[124:127]
	v_mfma_f32_16x16x32_bf16 v[92:95], v[140:143], v[148:151], v[92:95]
	v_mfma_f32_16x16x32_bf16 v[120:123], v[132:135], v[156:159], v[120:123]
	v_mfma_f32_16x16x32_bf16 v[88:91], v[140:143], v[156:159], v[88:91]
	v_mfma_f32_16x16x32_bf16 v[116:119], v[132:135], v[174:177], v[116:119]
	v_mfma_f32_16x16x32_bf16 v[84:87], v[140:143], v[174:177], v[84:87]
	v_mfma_f32_16x16x32_bf16 v[112:115], v[132:135], v[182:185], v[112:115]
	v_mfma_f32_16x16x32_bf16 v[80:83], v[140:143], v[182:185], v[80:83]
	s_barrier
	s_add_u32 s8, s6, 0x100
	s_addc_u32 s9, s7, 0
	s_cmp_eq_u32 s18, 28
	s_cselect_b32 s13, s39, s9
	s_cselect_b32 s12, s38, s8
	s_cselect_b32 s11, s41, s17
	s_cselect_b32 s10, s40, s16
	s_mov_b32 m0, s80
	v_lshl_add_u64 v[204:205], s[10:11], 0, v[164:165]
	ds_read_b128 v[186:189], v200
	ds_read_b128 v[190:193], v200 offset:1024
	ds_read_b128 v[194:197], v200 offset:2048
	ds_read_b128 v[208:211], v200 offset:3072
	global_load_lds_dwordx4 v[204:205], off
	v_lshl_add_u64 v[212:213], s[10:11], 0, v[166:167]
	s_mov_b32 m0, s81
	s_nop 0
	global_load_lds_dwordx4 v[212:213], off
	s_barrier
	s_waitcnt lgkmcnt(0)
	v_mfma_f32_16x16x32_bf16 v[60:63], v[186:189], v[144:147], v[60:63]
	v_mfma_f32_16x16x32_bf16 v[28:31], v[194:197], v[144:147], v[28:31]
	v_mfma_f32_16x16x32_bf16 v[56:59], v[186:189], v[152:155], v[56:59]
	v_mfma_f32_16x16x32_bf16 v[24:27], v[194:197], v[152:155], v[24:27]
	v_mfma_f32_16x16x32_bf16 v[52:55], v[186:189], v[160:163], v[52:55]
	v_mfma_f32_16x16x32_bf16 v[20:23], v[194:197], v[160:163], v[20:23]
	v_mfma_f32_16x16x32_bf16 v[48:51], v[186:189], v[178:181], v[48:51]
	v_mfma_f32_16x16x32_bf16 v[16:19], v[194:197], v[178:181], v[16:19]
	v_mfma_f32_16x16x32_bf16 v[60:63], v[190:193], v[148:151], v[60:63]
	v_mfma_f32_16x16x32_bf16 v[28:31], v[208:211], v[148:151], v[28:31]
	v_mfma_f32_16x16x32_bf16 v[56:59], v[190:193], v[156:159], v[56:59]
	v_mfma_f32_16x16x32_bf16 v[24:27], v[208:211], v[156:159], v[24:27]
	v_mfma_f32_16x16x32_bf16 v[52:55], v[190:193], v[174:177], v[52:55]
	v_mfma_f32_16x16x32_bf16 v[20:23], v[208:211], v[174:177], v[20:23]
	v_mfma_f32_16x16x32_bf16 v[48:51], v[190:193], v[182:185], v[48:51]
	v_mfma_f32_16x16x32_bf16 v[16:19], v[208:211], v[182:185], v[16:19]
	s_barrier
	s_mov_b32 m0, s21
	v_lshl_add_u64 v[214:215], s[12:13], 0, v[164:165]
	ds_read_b128 v[144:147], v199 offset:16384
	ds_read_b128 v[148:151], v199 offset:17408
	ds_read_b128 v[152:155], v199 offset:18432
	ds_read_b128 v[156:159], v199 offset:19456
	ds_read_b128 v[160:163], v199 offset:20480
	ds_read_b128 v[174:177], v199 offset:21504
	ds_read_b128 v[178:181], v199 offset:22528
	ds_read_b128 v[182:185], v199 offset:23552
	global_load_lds_dwordx4 v[214:215], off
	v_lshl_add_u64 v[216:217], s[12:13], 0, v[166:167]
	s_mov_b32 m0, s58
	s_nop 0
	global_load_lds_dwordx4 v[216:217], off
	s_barrier
	s_waitcnt lgkmcnt(0)
	v_mfma_f32_16x16x32_bf16 v[108:111], v[128:131], v[144:147], v[108:111]
	v_mfma_f32_16x16x32_bf16 v[76:79], v[136:139], v[144:147], v[76:79]
	v_mfma_f32_16x16x32_bf16 v[104:107], v[128:131], v[152:155], v[104:107]
	v_mfma_f32_16x16x32_bf16 v[72:75], v[136:139], v[152:155], v[72:75]
	v_mfma_f32_16x16x32_bf16 v[100:103], v[128:131], v[160:163], v[100:103]
	v_mfma_f32_16x16x32_bf16 v[68:71], v[136:139], v[160:163], v[68:71]
	v_mfma_f32_16x16x32_bf16 v[96:99], v[128:131], v[178:181], v[96:99]
	v_mfma_f32_16x16x32_bf16 v[64:67], v[136:139], v[178:181], v[64:67]
	v_mfma_f32_16x16x32_bf16 v[108:111], v[132:135], v[148:151], v[108:111]
	v_mfma_f32_16x16x32_bf16 v[76:79], v[140:143], v[148:151], v[76:79]
	v_mfma_f32_16x16x32_bf16 v[104:107], v[132:135], v[156:159], v[104:107]
	v_mfma_f32_16x16x32_bf16 v[72:75], v[140:143], v[156:159], v[72:75]
	v_mfma_f32_16x16x32_bf16 v[100:103], v[132:135], v[174:177], v[100:103]
	v_mfma_f32_16x16x32_bf16 v[68:71], v[140:143], v[174:177], v[68:71]
	v_mfma_f32_16x16x32_bf16 v[96:99], v[132:135], v[182:185], v[96:99]
	v_mfma_f32_16x16x32_bf16 v[64:67], v[140:143], v[182:185], v[64:67]
	s_barrier
	s_add_u32 s6, s10, 0x80000
	s_addc_u32 s7, s11, 0
	s_mov_b32 m0, s82
	v_lshl_add_u64 v[128:129], s[6:7], 0, v[164:165]
	global_load_lds_dwordx4 v[128:129], off
	v_lshl_add_u64 v[128:129], s[6:7], 0, v[166:167]
	s_mov_b32 m0, s83
	s_nop 0
	global_load_lds_dwordx4 v[128:129], off
	s_waitcnt vmcnt(6)
	s_barrier
; #define WAIT_V(n) asm volatile("s_waitcnt vmcnt(" #n ")" ::: "memory")
; #define WAIT_L(n) asm volatile("s_waitcnt lgkmcnt(" #n ")" ::: "memory")
; #define BAR __builtin_amdgcn_s_barrier()
; #define SCHED __builtin_amdgcn_sched_barrier(0)
; template <class Get, class Epi>
; DI void gemm_stream(LAS unsigned char* lds, const int K, const int ld, Get get, Epi epi) {
;     ...
;             WAIT_V(6); BAR; MMA(1, 1, At, B1); BAR;
;             LDB(B0, 1, 0); SCHED; LDA(At, 1, 0); STAGE(SAo(0, 1), a2 + hstep);
;             WAIT_L(8); BAR; WAIT_L(0); MMA(0, 0, At, B0); BAR; SCHED;
;             LDB(B1, 1, 1); STAGE(SBo(1, 0), b3);
;             BAR; WAIT_L(0); MMA(0, 1, At, B1); BAR;
;             LDA(At, 1, 1); STAGE(SAo(1, 0), a3);
;             BAR; WAIT_L(0); MMA(1, 0, At, B0); BAR; SCHED;
	v_mfma_f32_16x16x32_bf16 v[44:47], v[186:189], v[144:147], v[44:47]
	v_mfma_f32_16x16x32_bf16 v[12:15], v[194:197], v[144:147], v[12:15]
	v_mfma_f32_16x16x32_bf16 v[40:43], v[186:189], v[152:155], v[40:43]
	v_mfma_f32_16x16x32_bf16 v[8:11], v[194:197], v[152:155], v[8:11]
	v_mfma_f32_16x16x32_bf16 v[36:39], v[186:189], v[160:163], v[36:39]
	v_mfma_f32_16x16x32_bf16 v[4:7], v[194:197], v[160:163], v[4:7]
	v_mfma_f32_16x16x32_bf16 v[32:35], v[186:189], v[178:181], v[32:35]
	v_mfma_f32_16x16x32_bf16 v[0:3], v[194:197], v[178:181], v[0:3]
	v_mfma_f32_16x16x32_bf16 v[44:47], v[190:193], v[148:151], v[44:47]
	v_mfma_f32_16x16x32_bf16 v[12:15], v[208:211], v[148:151], v[12:15]
	v_mfma_f32_16x16x32_bf16 v[40:43], v[190:193], v[156:159], v[40:43]
	v_mfma_f32_16x16x32_bf16 v[8:11], v[208:211], v[156:159], v[8:11]
	v_mfma_f32_16x16x32_bf16 v[36:39], v[190:193], v[174:177], v[36:39]
	v_mfma_f32_16x16x32_bf16 v[4:7], v[208:211], v[174:177], v[4:7]
	v_mfma_f32_16x16x32_bf16 v[32:35], v[190:193], v[182:185], v[32:35]
	v_mfma_f32_16x16x32_bf16 v[0:3], v[208:211], v[182:185], v[0:3]
	s_barrier
	ds_read_b128 v[128:131], v201
	ds_read_b128 v[132:135], v201 offset:1024
	ds_read_b128 v[136:139], v201 offset:2048
	ds_read_b128 v[140:143], v201 offset:3072
	s_add_u32 s6, s12, 0x80000
	s_addc_u32 s7, s13, 0
	s_mov_b32 m0, s59
	v_lshl_add_u64 v[186:187], s[6:7], 0, v[164:165]
	ds_read_b128 v[144:147], v199 offset:32768
	ds_read_b128 v[148:151], v199 offset:33792
	ds_read_b128 v[152:155], v199 offset:34816
	ds_read_b128 v[156:159], v199 offset:35840
	ds_read_b128 v[160:163], v199 offset:36864
	ds_read_b128 v[174:177], v199 offset:37888
	ds_read_b128 v[178:181], v199 offset:38912
	ds_read_b128 v[182:185], v199 offset:39936
	global_load_lds_dwordx4 v[186:187], off
	v_lshl_add_u64 v[186:187], s[6:7], 0, v[166:167]
	s_mov_b32 m0, s60
	s_nop 0
	global_load_lds_dwordx4 v[186:187], off
	s_waitcnt lgkmcnt(8)
	s_barrier
	s_waitcnt lgkmcnt(0)
	v_mfma_f32_16x16x32_bf16 v[124:127], v[128:131], v[144:147], v[124:127]
	v_mfma_f32_16x16x32_bf16 v[92:95], v[136:139], v[144:147], v[92:95]
	v_mfma_f32_16x16x32_bf16 v[120:123], v[128:131], v[152:155], v[120:123]
	v_mfma_f32_16x16x32_bf16 v[88:91], v[136:139], v[152:155], v[88:91]
	v_mfma_f32_16x16x32_bf16 v[116:119], v[128:131], v[160:163], v[116:119]
	v_mfma_f32_16x16x32_bf16 v[84:87], v[136:139], v[160:163], v[84:87]
	v_mfma_f32_16x16x32_bf16 v[112:115], v[128:131], v[178:181], v[112:115]
	v_mfma_f32_16x16x32_bf16 v[80:83], v[136:139], v[178:181], v[80:83]
	v_mfma_f32_16x16x32_bf16 v[124:127], v[132:135], v[148:151], v[124:127]
	v_mfma_f32_16x16x32_bf16 v[92:95], v[140:143], v[148:151], v[92:95]
	v_mfma_f32_16x16x32_bf16 v[120:123], v[132:135], v[156:159], v[120:123]
	v_mfma_f32_16x16x32_bf16 v[88:91], v[140:143], v[156:159], v[88:91]
	v_mfma_f32_16x16x32_bf16 v[116:119], v[132:135], v[174:177], v[116:119]
	v_mfma_f32_16x16x32_bf16 v[84:87], v[140:143], v[174:177], v[84:87]
	v_mfma_f32_16x16x32_bf16 v[112:115], v[132:135], v[182:185], v[112:115]
	v_mfma_f32_16x16x32_bf16 v[80:83], v[140:143], v[182:185], v[80:83]
	s_barrier
	s_mov_b32 m0, s85
	v_lshl_add_u64 v[204:205], v[204:205], 0, s[0:1]
	ds_read_b128 v[186:189], v202
	ds_read_b128 v[190:193], v202 offset:1024
	ds_read_b128 v[194:197], v202 offset:2048
	ds_read_b128 v[208:211], v202 offset:3072
	global_load_lds_dwordx4 v[204:205], off
	v_lshl_add_u64 v[204:205], v[212:213], 0, s[0:1]
	s_mov_b32 m0, s96
	s_nop 0
	global_load_lds_dwordx4 v[204:205], off
	s_barrier
	s_waitcnt lgkmcnt(0)
	v_mfma_f32_16x16x32_bf16 v[60:63], v[186:189], v[144:147], v[60:63]
	v_mfma_f32_16x16x32_bf16 v[28:31], v[194:197], v[144:147], v[28:31]
	v_mfma_f32_16x16x32_bf16 v[56:59], v[186:189], v[152:155], v[56:59]
	v_mfma_f32_16x16x32_bf16 v[24:27], v[194:197], v[152:155], v[24:27]
	v_mfma_f32_16x16x32_bf16 v[52:55], v[186:189], v[160:163], v[52:55]
	v_mfma_f32_16x16x32_bf16 v[20:23], v[194:197], v[160:163], v[20:23]
	v_mfma_f32_16x16x32_bf16 v[48:51], v[186:189], v[178:181], v[48:51]
	v_mfma_f32_16x16x32_bf16 v[16:19], v[194:197], v[178:181], v[16:19]
	v_mfma_f32_16x16x32_bf16 v[60:63], v[190:193], v[148:151], v[60:63]
	v_mfma_f32_16x16x32_bf16 v[28:31], v[208:211], v[148:151], v[28:31]
	v_mfma_f32_16x16x32_bf16 v[56:59], v[190:193], v[156:159], v[56:59]
	v_mfma_f32_16x16x32_bf16 v[24:27], v[208:211], v[156:159], v[24:27]
	v_mfma_f32_16x16x32_bf16 v[52:55], v[190:193], v[174:177], v[52:55]
	v_mfma_f32_16x16x32_bf16 v[20:23], v[208:211], v[174:177], v[20:23]
	v_mfma_f32_16x16x32_bf16 v[48:51], v[190:193], v[182:185], v[48:51]
	v_mfma_f32_16x16x32_bf16 v[16:19], v[208:211], v[182:185], v[16:19]
	s_barrier
	s_mov_b32 m0, s61
	v_lshl_add_u64 v[204:205], v[214:215], 0, s[0:1]
	ds_read_b128 v[144:147], v199 offset:49152
	ds_read_b128 v[148:151], v199 offset:50176
	ds_read_b128 v[152:155], v199 offset:51200
	ds_read_b128 v[156:159], v199 offset:52224
	ds_read_b128 v[160:163], v199 offset:53248
	ds_read_b128 v[174:177], v199 offset:54272
	ds_read_b128 v[178:181], v199 offset:55296
	ds_read_b128 v[182:185], v199 offset:56320
	global_load_lds_dwordx4 v[204:205], off
	v_lshl_add_u64 v[204:205], v[216:217], 0, s[0:1]
	s_mov_b32 m0, s62
	s_nop 0
	global_load_lds_dwordx4 v[204:205], off
	s_barrier
; #define WAIT_V(n) asm volatile("s_waitcnt vmcnt(" #n ")" ::: "memory")
; #define WAIT_L(n) asm volatile("s_waitcnt lgkmcnt(" #n ")" ::: "memory")
; #define BAR __builtin_amdgcn_s_barrier()
; #define SCHED __builtin_amdgcn_sched_barrier(0)
; template <class Get, class Epi>
; DI void gemm_stream(LAS unsigned char* lds, const int K, const int ld, Get get, Epi epi) {
;     ...
;             BAR; WAIT_L(0); MMA(1, 0, At, B0); BAR; SCHED;
;             STAGE(SBo(1, 1), b3 + hstep);
;             WAIT_V(6); BAR; MMA(1, 1, At, B1); BAR;
;         }
; DI void epi_resid(const Acc& acc, const P& p, int brow, int bcol, int layer, int gch, bool from_input) {
;     ...
; #pragma unroll
;     for (int bj = 0; bj < 2; ++bj)
; #pragma unroll
;         for (int n = 0; n < 2; ++n) {
;             const int c0 = bcol + bj * 128 + wc * 32 + n * 16 + fq * 4;
;             const f32x4 g = *(const f32x4*)(gate + c0);
;             f32x4 xv[2][4];
; #pragma unroll
;             for (int ai = 0; ai < 2; ++ai)
; #pragma unroll
;                 for (int m = 0; m < 4; ++m) {
;                     const int r = brow + ai * 128 + wr * 64 + m * 16 + fr;
;                     const float* sp = (from_input ? inrow(p, r) : xrow(p, r)) + c0;
;                     xv[ai][m] = *(const f32x4*)sp;
;                 }
;             __builtin_amdgcn_sched_barrier(0);
; #pragma unroll
;             for (int ai = 0; ai < 2; ++ai)
; #pragma unroll
;                 for (int m = 0; m < 4; ++m) {
;                     const int r = brow + ai * 128 + wr * 64 + m * 16 + fr;
;                     *(f32x4*)(xrow(p, r) + c0) = xv[ai][m] + g * acc[ai][bj][m][n];
;                 }
;             __builtin_amdgcn_sched_barrier(0);
;         }
	s_waitcnt lgkmcnt(0)
	v_mfma_f32_16x16x32_bf16 v[108:111], v[128:131], v[144:147], v[108:111]
	v_mfma_f32_16x16x32_bf16 v[76:79], v[136:139], v[144:147], v[76:79]
	v_mfma_f32_16x16x32_bf16 v[104:107], v[128:131], v[152:155], v[104:107]
	v_mfma_f32_16x16x32_bf16 v[72:75], v[136:139], v[152:155], v[72:75]
	v_mfma_f32_16x16x32_bf16 v[100:103], v[128:131], v[160:163], v[100:103]
	v_mfma_f32_16x16x32_bf16 v[68:71], v[136:139], v[160:163], v[68:71]
	v_mfma_f32_16x16x32_bf16 v[96:99], v[128:131], v[178:181], v[96:99]
	v_mfma_f32_16x16x32_bf16 v[64:67], v[136:139], v[178:181], v[64:67]
	v_mfma_f32_16x16x32_bf16 v[108:111], v[132:135], v[148:151], v[108:111]
	v_mfma_f32_16x16x32_bf16 v[76:79], v[140:143], v[148:151], v[76:79]
	v_mfma_f32_16x16x32_bf16 v[104:107], v[132:135], v[156:159], v[104:107]
	v_mfma_f32_16x16x32_bf16 v[72:75], v[140:143], v[156:159], v[72:75]
	v_mfma_f32_16x16x32_bf16 v[100:103], v[132:135], v[174:177], v[100:103]
	v_mfma_f32_16x16x32_bf16 v[68:71], v[140:143], v[174:177], v[68:71]
	v_mfma_f32_16x16x32_bf16 v[96:99], v[132:135], v[182:185], v[96:99]
	v_mfma_f32_16x16x32_bf16 v[64:67], v[140:143], v[182:185], v[64:67]
	s_barrier
	s_add_u32 s6, s10, 0x80080
	s_addc_u32 s7, s11, 0
	s_mov_b32 m0, s97
	v_lshl_add_u64 v[128:129], s[6:7], 0, v[164:165]
	global_load_lds_dwordx4 v[128:129], off
	v_lshl_add_u64 v[128:129], s[6:7], 0, v[166:167]
	s_add_i32 m0, s97, 0x2000
	s_nop 0
	global_load_lds_dwordx4 v[128:129], off
	s_add_i32 s18, s18, 2
	s_add_u32 s16, s16, 0x100
	s_addc_u32 s17, s17, 0
	s_cmp_gt_u32 s18, 29
	s_mov_b64 s[6:7], s[8:9]
	s_waitcnt vmcnt(6)
	s_barrier
	v_mfma_f32_16x16x32_bf16 v[44:47], v[186:189], v[144:147], v[44:47]
	v_mfma_f32_16x16x32_bf16 v[12:15], v[194:197], v[144:147], v[12:15]
	v_mfma_f32_16x16x32_bf16 v[40:43], v[186:189], v[152:155], v[40:43]
	v_mfma_f32_16x16x32_bf16 v[8:11], v[194:197], v[152:155], v[8:11]
	v_mfma_f32_16x16x32_bf16 v[36:39], v[186:189], v[160:163], v[36:39]
	v_mfma_f32_16x16x32_bf16 v[4:7], v[194:197], v[160:163], v[4:7]
	v_mfma_f32_16x16x32_bf16 v[32:35], v[186:189], v[178:181], v[32:35]
	v_mfma_f32_16x16x32_bf16 v[0:3], v[194:197], v[178:181], v[0:3]
	v_mfma_f32_16x16x32_bf16 v[44:47], v[190:193], v[148:151], v[44:47]
	v_mfma_f32_16x16x32_bf16 v[12:15], v[208:211], v[148:151], v[12:15]
	v_mfma_f32_16x16x32_bf16 v[40:43], v[190:193], v[156:159], v[40:43]
	v_mfma_f32_16x16x32_bf16 v[8:11], v[208:211], v[156:159], v[8:11]
	v_mfma_f32_16x16x32_bf16 v[36:39], v[190:193], v[174:177], v[36:39]
	v_mfma_f32_16x16x32_bf16 v[4:7], v[208:211], v[174:177], v[4:7]
	v_mfma_f32_16x16x32_bf16 v[32:35], v[190:193], v[182:185], v[32:35]
	v_mfma_f32_16x16x32_bf16 v[0:3], v[208:211], v[182:185], v[0:3]
	s_barrier
	s_cbranch_scc0 .LBB0_1238
	s_lshl_b32 s12, s15, 21
	s_lshl_b32 s13, s14, 10
	s_lshr_b32 s16, s15, 4
	s_add_u32 s12, s12, s13
	s_mul_i32 s16, s16, 6
	s_add_i32 s16, s16, 2
	s_lshl_b32 s16, s16, 13
	s_add_u32 s16, s16, s13
	s_add_u32 s10, s26, s16
	s_addc_u32 s11, s27, 0
	s_add_u32 s8, s52, s12
	s_addc_u32 s9, s53, 0
	s_add_u32 s6, s24, s12
	s_addc_u32 s7, s25, 0
	v_lshrrev_b32_e32 v224, 6, v206
	v_and_b32_e32 v225, 3, v224
	v_lshrrev_b32_e32 v224, 2, v224
	v_and_b32_e32 v205, 15, v206
	v_bfe_u32 v226, v206, 4, 2
	v_lshl_add_u32 v225, v225, 3, v226
	v_lshl_add_u32 v224, v224, 6, v205
	v_lshlrev_b32_e32 v205, 4, v225
	v_lshl_add_u32 v203, v224, 13, v205
	v_mov_b32_e32 v204, v203
	global_load_dwordx4 v[128:131], v205, s[10:11] offset:0
	global_load_dwordx4 v[132:135], v205, s[10:11] offset:64
	global_load_dwordx4 v[136:139], v205, s[10:11] offset:512
	global_load_dwordx4 v[140:143], v205, s[10:11] offset:576
	global_load_dwordx4 v[144:147], v203, s[8:9] offset:0
	global_load_dwordx4 v[148:151], v203, s[8:9] offset:64
	global_load_dwordx4 v[152:155], v203, s[8:9] offset:512
	global_load_dwordx4 v[156:159], v203, s[8:9] offset:576
	v_add_u32_e32 v203, 0x20000, v203
	global_load_dwordx4 v[160:163], v203, s[8:9] offset:0
	global_load_dwordx4 v[174:177], v203, s[8:9] offset:64
	global_load_dwordx4 v[178:181], v203, s[8:9] offset:512
	global_load_dwordx4 v[182:185], v203, s[8:9] offset:576
	v_add_u32_e32 v203, 0x20000, v203
	global_load_dwordx4 v[186:189], v203, s[8:9] offset:0
	global_load_dwordx4 v[190:193], v203, s[8:9] offset:64
	global_load_dwordx4 v[194:197], v203, s[8:9] offset:512
	global_load_dwordx4 v[208:211], v203, s[8:9] offset:576
	v_add_u32_e32 v203, 0x20000, v203
	global_load_dwordx4 v[212:215], v203, s[8:9] offset:0
	global_load_dwordx4 v[216:219], v203, s[8:9] offset:64
	global_load_dwordx4 v[220:223], v203, s[8:9] offset:512
	global_load_dwordx4 v[224:227], v203, s[8:9] offset:576
	v_add_u32_e32 v203, 0xa0000, v203
	s_waitcnt vmcnt(12)
	v_pk_fma_f32 v[124:125], v[124:125], v[128:129], v[144:145]
	v_pk_fma_f32 v[126:127], v[126:127], v[130:131], v[146:147]
	v_pk_fma_f32 v[92:93], v[92:93], v[132:133], v[148:149]
	v_pk_fma_f32 v[94:95], v[94:95], v[134:135], v[150:151]
	v_pk_fma_f32 v[60:61], v[60:61], v[136:137], v[152:153]
	v_pk_fma_f32 v[62:63], v[62:63], v[138:139], v[154:155]
	v_pk_fma_f32 v[28:29], v[28:29], v[140:141], v[156:157]
	v_pk_fma_f32 v[30:31], v[30:31], v[142:143], v[158:159]
	global_store_dwordx4 v204, v[124:127], s[6:7] offset:0
	global_store_dwordx4 v204, v[92:95], s[6:7] offset:64
	global_store_dwordx4 v204, v[60:63], s[6:7] offset:512
	global_store_dwordx4 v204, v[28:31], s[6:7] offset:576
	v_add_u32_e32 v204, 0x20000, v204
	global_load_dwordx4 v[144:147], v203, s[8:9] offset:0
	global_load_dwordx4 v[148:151], v203, s[8:9] offset:64
	global_load_dwordx4 v[152:155], v203, s[8:9] offset:512
	global_load_dwordx4 v[156:159], v203, s[8:9] offset:576
	v_add_u32_e32 v203, 0x20000, v203
	s_waitcnt vmcnt(16)
; DI void epi_resid(const Acc& acc, const P& p, int brow, int bcol, int layer, int gch, bool from_input) {
;     ...
; #pragma unroll
;     for (int bj = 0; bj < 2; ++bj)
; #pragma unroll
;         for (int n = 0; n < 2; ++n) {
;             const int c0 = bcol + bj * 128 + wc * 32 + n * 16 + fq * 4;
;             const f32x4 g = *(const f32x4*)(gate + c0);
;             f32x4 xv[2][4];
; #pragma unroll
;             for (int ai = 0; ai < 2; ++ai)
; #pragma unroll
;                 for (int m = 0; m < 4; ++m) {
;                     const int r = brow + ai * 128 + wr * 64 + m * 16 + fr;
;                     const float* sp = (from_input ? inrow(p, r) : xrow(p, r)) + c0;
;                     xv[ai][m] = *(const f32x4*)sp;
;                 }
;             __builtin_amdgcn_sched_barrier(0);
; #pragma unroll
;             for (int ai = 0; ai < 2; ++ai)
; #pragma unroll
;                 for (int m = 0; m < 4; ++m) {
;                     const int r = brow + ai * 128 + wr * 64 + m * 16 + fr;
;                     *(f32x4*)(xrow(p, r) + c0) = xv[ai][m] + g * acc[ai][bj][m][n];
;                 }
;             __builtin_amdgcn_sched_barrier(0);
;         }
	v_pk_fma_f32 v[120:121], v[120:121], v[128:129], v[160:161]
	v_pk_fma_f32 v[122:123], v[122:123], v[130:131], v[162:163]
	v_pk_fma_f32 v[88:89], v[88:89], v[132:133], v[174:175]
	v_pk_fma_f32 v[90:91], v[90:91], v[134:135], v[176:177]
	v_pk_fma_f32 v[56:57], v[56:57], v[136:137], v[178:179]
	v_pk_fma_f32 v[58:59], v[58:59], v[138:139], v[180:181]
	v_pk_fma_f32 v[24:25], v[24:25], v[140:141], v[182:183]
	v_pk_fma_f32 v[26:27], v[26:27], v[142:143], v[184:185]
	global_store_dwordx4 v204, v[120:123], s[6:7] offset:0
	global_store_dwordx4 v204, v[88:91], s[6:7] offset:64
	global_store_dwordx4 v204, v[56:59], s[6:7] offset:512
	global_store_dwordx4 v204, v[24:27], s[6:7] offset:576
	v_add_u32_e32 v204, 0x20000, v204
	global_load_dwordx4 v[160:163], v203, s[8:9] offset:0
	global_load_dwordx4 v[174:177], v203, s[8:9] offset:64
	global_load_dwordx4 v[178:181], v203, s[8:9] offset:512
	global_load_dwordx4 v[182:185], v203, s[8:9] offset:576
	v_add_u32_e32 v203, 0x20000, v203
	s_waitcnt vmcnt(20)
	v_pk_fma_f32 v[116:117], v[116:117], v[128:129], v[186:187]
	v_pk_fma_f32 v[118:119], v[118:119], v[130:131], v[188:189]
	v_pk_fma_f32 v[84:85], v[84:85], v[132:133], v[190:191]
	v_pk_fma_f32 v[86:87], v[86:87], v[134:135], v[192:193]
	v_pk_fma_f32 v[52:53], v[52:53], v[136:137], v[194:195]
	v_pk_fma_f32 v[54:55], v[54:55], v[138:139], v[196:197]
	v_pk_fma_f32 v[20:21], v[20:21], v[140:141], v[208:209]
	v_pk_fma_f32 v[22:23], v[22:23], v[142:143], v[210:211]
	global_store_dwordx4 v204, v[116:119], s[6:7] offset:0
	global_store_dwordx4 v204, v[84:87], s[6:7] offset:64
	global_store_dwordx4 v204, v[52:55], s[6:7] offset:512
	global_store_dwordx4 v204, v[20:23], s[6:7] offset:576
	v_add_u32_e32 v204, 0x20000, v204
	global_load_dwordx4 v[186:189], v203, s[8:9] offset:0
	global_load_dwordx4 v[190:193], v203, s[8:9] offset:64
	global_load_dwordx4 v[194:197], v203, s[8:9] offset:512
	global_load_dwordx4 v[208:211], v203, s[8:9] offset:576
	v_add_u32_e32 v203, 0x20000, v203
	s_waitcnt vmcnt(24)
	v_pk_fma_f32 v[112:113], v[112:113], v[128:129], v[212:213]
	v_pk_fma_f32 v[114:115], v[114:115], v[130:131], v[214:215]
	v_pk_fma_f32 v[80:81], v[80:81], v[132:133], v[216:217]
	v_pk_fma_f32 v[82:83], v[82:83], v[134:135], v[218:219]
	v_pk_fma_f32 v[48:49], v[48:49], v[136:137], v[220:221]
	v_pk_fma_f32 v[50:51], v[50:51], v[138:139], v[222:223]
	v_pk_fma_f32 v[16:17], v[16:17], v[140:141], v[224:225]
	v_pk_fma_f32 v[18:19], v[18:19], v[142:143], v[226:227]
	global_store_dwordx4 v204, v[112:115], s[6:7] offset:0
	global_store_dwordx4 v204, v[80:83], s[6:7] offset:64
	global_store_dwordx4 v204, v[48:51], s[6:7] offset:512
	global_store_dwordx4 v204, v[16:19], s[6:7] offset:576
	v_add_u32_e32 v204, 0xa0000, v204
	global_load_dwordx4 v[212:215], v203, s[8:9] offset:0
	global_load_dwordx4 v[216:219], v203, s[8:9] offset:64
	global_load_dwordx4 v[220:223], v203, s[8:9] offset:512
	global_load_dwordx4 v[224:227], v203, s[8:9] offset:576
	s_waitcnt vmcnt(24)
	v_pk_fma_f32 v[108:109], v[108:109], v[128:129], v[144:145]
	v_pk_fma_f32 v[110:111], v[110:111], v[130:131], v[146:147]
	v_pk_fma_f32 v[76:77], v[76:77], v[132:133], v[148:149]
	v_pk_fma_f32 v[78:79], v[78:79], v[134:135], v[150:151]
	v_pk_fma_f32 v[44:45], v[44:45], v[136:137], v[152:153]
	v_pk_fma_f32 v[46:47], v[46:47], v[138:139], v[154:155]
	v_pk_fma_f32 v[12:13], v[12:13], v[140:141], v[156:157]
	v_pk_fma_f32 v[14:15], v[14:15], v[142:143], v[158:159]
	global_store_dwordx4 v204, v[108:111], s[6:7] offset:0
	global_store_dwordx4 v204, v[76:79], s[6:7] offset:64
	global_store_dwordx4 v204, v[44:47], s[6:7] offset:512
	global_store_dwordx4 v204, v[12:15], s[6:7] offset:576
	v_add_u32_e32 v204, 0x20000, v204
	s_waitcnt vmcnt(20)
	v_pk_fma_f32 v[104:105], v[104:105], v[128:129], v[160:161]
	v_pk_fma_f32 v[106:107], v[106:107], v[130:131], v[162:163]
	v_pk_fma_f32 v[72:73], v[72:73], v[132:133], v[174:175]
	v_pk_fma_f32 v[74:75], v[74:75], v[134:135], v[176:177]
	v_pk_fma_f32 v[40:41], v[40:41], v[136:137], v[178:179]
	v_pk_fma_f32 v[42:43], v[42:43], v[138:139], v[180:181]
	v_pk_fma_f32 v[8:9], v[8:9], v[140:141], v[182:183]
	v_pk_fma_f32 v[10:11], v[10:11], v[142:143], v[184:185]
	global_store_dwordx4 v204, v[104:107], s[6:7] offset:0
	global_store_dwordx4 v204, v[72:75], s[6:7] offset:64
	global_store_dwordx4 v204, v[40:43], s[6:7] offset:512
	global_store_dwordx4 v204, v[8:11], s[6:7] offset:576
	v_add_u32_e32 v204, 0x20000, v204
	s_waitcnt vmcnt(16)
	v_pk_fma_f32 v[100:101], v[100:101], v[128:129], v[186:187]
	v_pk_fma_f32 v[102:103], v[102:103], v[130:131], v[188:189]
	v_pk_fma_f32 v[68:69], v[68:69], v[132:133], v[190:191]
	v_pk_fma_f32 v[70:71], v[70:71], v[134:135], v[192:193]
	v_pk_fma_f32 v[36:37], v[36:37], v[136:137], v[194:195]
	v_pk_fma_f32 v[38:39], v[38:39], v[138:139], v[196:197]
	v_pk_fma_f32 v[4:5], v[4:5], v[140:141], v[208:209]
	v_pk_fma_f32 v[6:7], v[6:7], v[142:143], v[210:211]
	global_store_dwordx4 v204, v[100:103], s[6:7] offset:0
	global_store_dwordx4 v204, v[68:71], s[6:7] offset:64
	global_store_dwordx4 v204, v[36:39], s[6:7] offset:512
	global_store_dwordx4 v204, v[4:7], s[6:7] offset:576
	v_add_u32_e32 v204, 0x20000, v204
	s_waitcnt vmcnt(12)
	v_pk_fma_f32 v[96:97], v[96:97], v[128:129], v[212:213]
	v_pk_fma_f32 v[98:99], v[98:99], v[130:131], v[214:215]
	v_pk_fma_f32 v[64:65], v[64:65], v[132:133], v[216:217]
	v_pk_fma_f32 v[66:67], v[66:67], v[134:135], v[218:219]
	v_pk_fma_f32 v[32:33], v[32:33], v[136:137], v[220:221]
	v_pk_fma_f32 v[34:35], v[34:35], v[138:139], v[222:223]
	v_pk_fma_f32 v[0:1], v[0:1], v[140:141], v[224:225]
	v_pk_fma_f32 v[2:3], v[2:3], v[142:143], v[226:227]
	global_store_dwordx4 v204, v[96:99], s[6:7] offset:0
	global_store_dwordx4 v204, v[64:67], s[6:7] offset:64
	global_store_dwordx4 v204, v[32:35], s[6:7] offset:512
	global_store_dwordx4 v204, v[0:3], s[6:7] offset:576
	s_branch .Lresid_latch_wout0

; #define WAIT_V(n) asm volatile("s_waitcnt vmcnt(" #n ")" ::: "memory")
; #define WAIT_L(n) asm volatile("s_waitcnt lgkmcnt(" #n ")" ::: "memory")
; #define BAR __builtin_amdgcn_s_barrier()
; #define SCHED __builtin_amdgcn_sched_barrier(0)
; template <class Get, class Epi>
; DI void gemm_stream(LAS unsigned char* lds, const int K, const int ld, Get get, Epi epi) {
;     ...
;             const bool last = (t == nt - 2);
;             const char* a1 = cA + (size_t)(t + 1) * kstep;
;             const char* a2 = last ? nA : cA + (size_t)(t + 2) * kstep;
;             const char* b2 = last ? nB : cB + (size_t)(t + 2) * kstep;
;             const char* a3 = a2 + kstep;
;             const char* b3 = b2 + kstep;
;             LDB(B0, 0, 0); SCHED; LDA(At, 0, 0); STAGE(SAo(1, 1), a1 + hstep);
;             WAIT_L(8); BAR; WAIT_L(0); MMA(0, 0, At, B0); BAR; SCHED;
;             LDB(B1, 0, 1); STAGE(SBo(0, 0), b2);
;             BAR; WAIT_L(0); MMA(0, 1, At, B1); BAR;
;             LDA(At, 0, 1); STAGE(SAo(0, 0), a2);
;             BAR; WAIT_L(0); MMA(1, 0, At, B0); BAR; SCHED;
;             STAGE(SBo(0, 1), b2 + hstep);
;             WAIT_V(6); BAR; MMA(1, 1, At, B1); BAR;
.LBB0_1630:
	ds_read_b128 v[148:151], v142
	ds_read_b128 v[152:155], v142 offset:1024
	ds_read_b128 v[156:159], v142 offset:2048
	ds_read_b128 v[160:163], v142 offset:3072
	s_mov_b32 m0, s28
	v_lshl_add_u64 v[140:141], s[10:11], 0, v[134:135]
	ds_read_b128 v[164:167], v143
	ds_read_b128 v[168:171], v143 offset:1024
	ds_read_b128 v[172:175], v143 offset:2048
	ds_read_b128 v[176:179], v143 offset:3072
	ds_read_b128 v[180:183], v143 offset:4096
	ds_read_b128 v[184:187], v143 offset:5120
	ds_read_b128 v[188:191], v143 offset:6144
	ds_read_b128 v[192:195], v143 offset:7168
	global_load_lds_dwordx4 v[140:141], off
	v_lshl_add_u64 v[140:141], s[10:11], 0, v[136:137]
	s_mov_b32 m0, s29
	s_nop 0
	global_load_lds_dwordx4 v[140:141], off
	s_waitcnt lgkmcnt(8)
	s_barrier
	s_waitcnt lgkmcnt(0)
	v_mfma_f32_16x16x32_bf16 v[124:127], v[148:151], v[164:167], v[124:127]
	v_mfma_f32_16x16x32_bf16 v[116:119], v[156:159], v[164:167], v[116:119]
	v_mfma_f32_16x16x32_bf16 v[108:111], v[148:151], v[172:175], v[108:111]
	v_mfma_f32_16x16x32_bf16 v[100:103], v[156:159], v[172:175], v[100:103]
	v_mfma_f32_16x16x32_bf16 v[92:95], v[148:151], v[180:183], v[92:95]
	v_mfma_f32_16x16x32_bf16 v[84:87], v[156:159], v[180:183], v[84:87]
	v_mfma_f32_16x16x32_bf16 v[76:79], v[148:151], v[188:191], v[76:79]
	v_mfma_f32_16x16x32_bf16 v[68:71], v[156:159], v[188:191], v[68:71]
	v_mfma_f32_16x16x32_bf16 v[124:127], v[152:155], v[168:171], v[124:127]
	v_mfma_f32_16x16x32_bf16 v[116:119], v[160:163], v[168:171], v[116:119]
	v_mfma_f32_16x16x32_bf16 v[108:111], v[152:155], v[176:179], v[108:111]
	v_mfma_f32_16x16x32_bf16 v[100:103], v[160:163], v[176:179], v[100:103]
	v_mfma_f32_16x16x32_bf16 v[92:95], v[152:155], v[184:187], v[92:95]
	v_mfma_f32_16x16x32_bf16 v[84:87], v[160:163], v[184:187], v[84:87]
	v_mfma_f32_16x16x32_bf16 v[76:79], v[152:155], v[192:195], v[76:79]
	v_mfma_f32_16x16x32_bf16 v[68:71], v[160:163], v[192:195], v[68:71]
	s_barrier
	s_add_u32 s12, s10, 0xfff80080
	s_addc_u32 s13, s11, -1
	s_cmp_eq_u32 s59, 28
	s_cselect_b32 s15, s7, s13
	s_cselect_b32 s14, s6, s12
	s_cselect_b32 s13, s9, s58
	s_cselect_b32 s12, s8, s57
	s_mov_b32 m0, s35
	v_lshl_add_u64 v[140:141], s[12:13], 0, v[130:131]
	ds_read_b128 v[196:199], v144
	ds_read_b128 v[200:203], v144 offset:1024
	ds_read_b128 v[208:211], v144 offset:2048
	ds_read_b128 v[212:215], v144 offset:3072
	global_load_lds_dwordx4 v[140:141], off
	v_lshl_add_u64 v[204:205], s[12:13], 0, v[128:129]
	s_mov_b32 m0, s36
	s_nop 0
	global_load_lds_dwordx4 v[204:205], off
	s_barrier
	s_waitcnt lgkmcnt(0)
	v_mfma_f32_16x16x32_bf16 v[120:123], v[196:199], v[164:167], v[120:123]
	v_mfma_f32_16x16x32_bf16 v[112:115], v[208:211], v[164:167], v[112:115]
	v_mfma_f32_16x16x32_bf16 v[104:107], v[196:199], v[172:175], v[104:107]
	v_mfma_f32_16x16x32_bf16 v[96:99], v[208:211], v[172:175], v[96:99]
	v_mfma_f32_16x16x32_bf16 v[88:91], v[196:199], v[180:183], v[88:91]
	v_mfma_f32_16x16x32_bf16 v[80:83], v[208:211], v[180:183], v[80:83]
	v_mfma_f32_16x16x32_bf16 v[72:75], v[196:199], v[188:191], v[72:75]
	v_mfma_f32_16x16x32_bf16 v[64:67], v[208:211], v[188:191], v[64:67]
	v_mfma_f32_16x16x32_bf16 v[120:123], v[200:203], v[168:171], v[120:123]
	v_mfma_f32_16x16x32_bf16 v[112:115], v[212:215], v[168:171], v[112:115]
	v_mfma_f32_16x16x32_bf16 v[104:107], v[200:203], v[176:179], v[104:107]
	v_mfma_f32_16x16x32_bf16 v[96:99], v[212:215], v[176:179], v[96:99]
	v_mfma_f32_16x16x32_bf16 v[88:91], v[200:203], v[184:187], v[88:91]
	v_mfma_f32_16x16x32_bf16 v[80:83], v[212:215], v[184:187], v[80:83]
	v_mfma_f32_16x16x32_bf16 v[72:75], v[200:203], v[192:195], v[72:75]
	v_mfma_f32_16x16x32_bf16 v[64:67], v[212:215], v[192:195], v[64:67]
	s_barrier
	s_mov_b32 m0, s3
	v_lshl_add_u64 v[216:217], s[14:15], 0, v[130:131]
	ds_read_b128 v[164:167], v143 offset:16384
	ds_read_b128 v[168:171], v143 offset:17408
	ds_read_b128 v[172:175], v143 offset:18432
	ds_read_b128 v[176:179], v143 offset:19456
	ds_read_b128 v[180:183], v143 offset:20480
	ds_read_b128 v[184:187], v143 offset:21504
	ds_read_b128 v[188:191], v143 offset:22528
	ds_read_b128 v[192:195], v143 offset:23552
	global_load_lds_dwordx4 v[216:217], off
	v_lshl_add_u64 v[218:219], s[14:15], 0, v[128:129]
	s_mov_b32 m0, s16
	s_nop 0
	global_load_lds_dwordx4 v[218:219], off
	s_barrier
	s_waitcnt lgkmcnt(0)
	v_mfma_f32_16x16x32_bf16 v[60:63], v[148:151], v[164:167], v[60:63]
	v_mfma_f32_16x16x32_bf16 v[52:55], v[156:159], v[164:167], v[52:55]
	v_mfma_f32_16x16x32_bf16 v[44:47], v[148:151], v[172:175], v[44:47]
	v_mfma_f32_16x16x32_bf16 v[36:39], v[156:159], v[172:175], v[36:39]
	v_mfma_f32_16x16x32_bf16 v[28:31], v[148:151], v[180:183], v[28:31]
	v_mfma_f32_16x16x32_bf16 v[20:23], v[156:159], v[180:183], v[20:23]
	v_mfma_f32_16x16x32_bf16 v[12:15], v[148:151], v[188:191], v[12:15]
	v_mfma_f32_16x16x32_bf16 v[4:7], v[156:159], v[188:191], v[4:7]
	v_mfma_f32_16x16x32_bf16 v[60:63], v[152:155], v[168:171], v[60:63]
	v_mfma_f32_16x16x32_bf16 v[52:55], v[160:163], v[168:171], v[52:55]
	v_mfma_f32_16x16x32_bf16 v[44:47], v[152:155], v[176:179], v[44:47]
	v_mfma_f32_16x16x32_bf16 v[36:39], v[160:163], v[176:179], v[36:39]
	v_mfma_f32_16x16x32_bf16 v[28:31], v[152:155], v[184:187], v[28:31]
	v_mfma_f32_16x16x32_bf16 v[20:23], v[160:163], v[184:187], v[20:23]
	v_mfma_f32_16x16x32_bf16 v[12:15], v[152:155], v[192:195], v[12:15]
	v_mfma_f32_16x16x32_bf16 v[4:7], v[160:163], v[192:195], v[4:7]
	s_barrier
	s_add_u32 s60, s12, 0x80000
	s_addc_u32 s61, s13, 0
	s_mov_b32 m0, s37
	v_lshl_add_u64 v[148:149], s[60:61], 0, v[130:131]
	global_load_lds_dwordx4 v[148:149], off
	v_lshl_add_u64 v[148:149], s[60:61], 0, v[128:129]
	s_mov_b32 m0, s38
	s_nop 0
	global_load_lds_dwordx4 v[148:149], off
	s_waitcnt vmcnt(6)
	s_barrier
; #define WAIT_V(n) asm volatile("s_waitcnt vmcnt(" #n ")" ::: "memory")
; #define WAIT_L(n) asm volatile("s_waitcnt lgkmcnt(" #n ")" ::: "memory")
; #define BAR __builtin_amdgcn_s_barrier()
; #define SCHED __builtin_amdgcn_sched_barrier(0)
; template <class Get, class Epi>
; DI void gemm_stream(LAS unsigned char* lds, const int K, const int ld, Get get, Epi epi) {
;     ...
;             WAIT_V(6); BAR; MMA(1, 1, At, B1); BAR;
;             LDB(B0, 1, 0); SCHED; LDA(At, 1, 0); STAGE(SAo(0, 1), a2 + hstep);
;             WAIT_L(8); BAR; WAIT_L(0); MMA(0, 0, At, B0); BAR; SCHED;
;             LDB(B1, 1, 1); STAGE(SBo(1, 0), b3);
;             BAR; WAIT_L(0); MMA(0, 1, At, B1); BAR;
;             LDA(At, 1, 1); STAGE(SAo(1, 0), a3);
;             BAR; WAIT_L(0); MMA(1, 0, At, B0); BAR; SCHED;
	v_mfma_f32_16x16x32_bf16 v[56:59], v[196:199], v[164:167], v[56:59]
	v_mfma_f32_16x16x32_bf16 v[48:51], v[208:211], v[164:167], v[48:51]
	v_mfma_f32_16x16x32_bf16 v[40:43], v[196:199], v[172:175], v[40:43]
	v_mfma_f32_16x16x32_bf16 v[32:35], v[208:211], v[172:175], v[32:35]
	v_mfma_f32_16x16x32_bf16 v[24:27], v[196:199], v[180:183], v[24:27]
	v_mfma_f32_16x16x32_bf16 v[16:19], v[208:211], v[180:183], v[16:19]
	v_mfma_f32_16x16x32_bf16 v[8:11], v[196:199], v[188:191], v[8:11]
	v_mfma_f32_16x16x32_bf16 v[0:3], v[208:211], v[188:191], v[0:3]
	v_mfma_f32_16x16x32_bf16 v[56:59], v[200:203], v[168:171], v[56:59]
	v_mfma_f32_16x16x32_bf16 v[48:51], v[212:215], v[168:171], v[48:51]
	v_mfma_f32_16x16x32_bf16 v[40:43], v[200:203], v[176:179], v[40:43]
	v_mfma_f32_16x16x32_bf16 v[32:35], v[212:215], v[176:179], v[32:35]
	v_mfma_f32_16x16x32_bf16 v[24:27], v[200:203], v[184:187], v[24:27]
	v_mfma_f32_16x16x32_bf16 v[16:19], v[212:215], v[184:187], v[16:19]
	v_mfma_f32_16x16x32_bf16 v[8:11], v[200:203], v[192:195], v[8:11]
	v_mfma_f32_16x16x32_bf16 v[0:3], v[212:215], v[192:195], v[0:3]
	s_barrier
	ds_read_b128 v[148:151], v145
	ds_read_b128 v[152:155], v145 offset:1024
	ds_read_b128 v[156:159], v145 offset:2048
	ds_read_b128 v[160:163], v145 offset:3072
	s_add_u32 s14, s14, 0x80000
	s_addc_u32 s15, s15, 0
	s_mov_b32 m0, s17
	v_lshl_add_u64 v[196:197], s[14:15], 0, v[130:131]
	ds_read_b128 v[164:167], v143 offset:32768
	ds_read_b128 v[168:171], v143 offset:33792
	ds_read_b128 v[172:175], v143 offset:34816
	ds_read_b128 v[176:179], v143 offset:35840
	ds_read_b128 v[180:183], v143 offset:36864
	ds_read_b128 v[184:187], v143 offset:37888
	ds_read_b128 v[188:191], v143 offset:38912
	ds_read_b128 v[192:195], v143 offset:39936
	global_load_lds_dwordx4 v[196:197], off
	v_lshl_add_u64 v[196:197], s[14:15], 0, v[128:129]
	s_mov_b32 m0, s18
	s_nop 0
	global_load_lds_dwordx4 v[196:197], off
	s_waitcnt lgkmcnt(8)
	s_barrier
	s_waitcnt lgkmcnt(0)
	v_mfma_f32_16x16x32_bf16 v[124:127], v[148:151], v[164:167], v[124:127]
	v_mfma_f32_16x16x32_bf16 v[116:119], v[156:159], v[164:167], v[116:119]
	v_mfma_f32_16x16x32_bf16 v[108:111], v[148:151], v[172:175], v[108:111]
	v_mfma_f32_16x16x32_bf16 v[100:103], v[156:159], v[172:175], v[100:103]
	v_mfma_f32_16x16x32_bf16 v[92:95], v[148:151], v[180:183], v[92:95]
	v_mfma_f32_16x16x32_bf16 v[84:87], v[156:159], v[180:183], v[84:87]
	v_mfma_f32_16x16x32_bf16 v[76:79], v[148:151], v[188:191], v[76:79]
	v_mfma_f32_16x16x32_bf16 v[68:71], v[156:159], v[188:191], v[68:71]
	v_mfma_f32_16x16x32_bf16 v[124:127], v[152:155], v[168:171], v[124:127]
	v_mfma_f32_16x16x32_bf16 v[116:119], v[160:163], v[168:171], v[116:119]
	v_mfma_f32_16x16x32_bf16 v[108:111], v[152:155], v[176:179], v[108:111]
	v_mfma_f32_16x16x32_bf16 v[100:103], v[160:163], v[176:179], v[100:103]
	v_mfma_f32_16x16x32_bf16 v[92:95], v[152:155], v[184:187], v[92:95]
	v_mfma_f32_16x16x32_bf16 v[84:87], v[160:163], v[184:187], v[84:87]
	v_mfma_f32_16x16x32_bf16 v[76:79], v[152:155], v[192:195], v[76:79]
	v_mfma_f32_16x16x32_bf16 v[68:71], v[160:163], v[192:195], v[68:71]
	s_barrier
	s_mov_b32 m0, s39
	v_lshl_add_u64 v[140:141], v[140:141], 0, s[0:1]
	ds_read_b128 v[196:199], v146
	ds_read_b128 v[200:203], v146 offset:1024
	ds_read_b128 v[208:211], v146 offset:2048
	ds_read_b128 v[212:215], v146 offset:3072
	global_load_lds_dwordx4 v[140:141], off
	v_lshl_add_u64 v[140:141], v[204:205], 0, s[0:1]
	s_mov_b32 m0, s40
	s_nop 0
	global_load_lds_dwordx4 v[140:141], off
	s_barrier
	s_waitcnt lgkmcnt(0)
	v_mfma_f32_16x16x32_bf16 v[120:123], v[196:199], v[164:167], v[120:123]
	v_mfma_f32_16x16x32_bf16 v[112:115], v[208:211], v[164:167], v[112:115]
	v_mfma_f32_16x16x32_bf16 v[104:107], v[196:199], v[172:175], v[104:107]
	v_mfma_f32_16x16x32_bf16 v[96:99], v[208:211], v[172:175], v[96:99]
	v_mfma_f32_16x16x32_bf16 v[88:91], v[196:199], v[180:183], v[88:91]
	v_mfma_f32_16x16x32_bf16 v[80:83], v[208:211], v[180:183], v[80:83]
	v_mfma_f32_16x16x32_bf16 v[72:75], v[196:199], v[188:191], v[72:75]
	v_mfma_f32_16x16x32_bf16 v[64:67], v[208:211], v[188:191], v[64:67]
	v_mfma_f32_16x16x32_bf16 v[120:123], v[200:203], v[168:171], v[120:123]
	v_mfma_f32_16x16x32_bf16 v[112:115], v[212:215], v[168:171], v[112:115]
	v_mfma_f32_16x16x32_bf16 v[104:107], v[200:203], v[176:179], v[104:107]
	v_mfma_f32_16x16x32_bf16 v[96:99], v[212:215], v[176:179], v[96:99]
	v_mfma_f32_16x16x32_bf16 v[88:91], v[200:203], v[184:187], v[88:91]
	v_mfma_f32_16x16x32_bf16 v[80:83], v[212:215], v[184:187], v[80:83]
	v_mfma_f32_16x16x32_bf16 v[72:75], v[200:203], v[192:195], v[72:75]
	v_mfma_f32_16x16x32_bf16 v[64:67], v[212:215], v[192:195], v[64:67]
	s_barrier
	s_mov_b32 m0, s20
	v_lshl_add_u64 v[140:141], v[216:217], 0, s[0:1]
	ds_read_b128 v[164:167], v143 offset:49152
	ds_read_b128 v[168:171], v143 offset:50176
	ds_read_b128 v[172:175], v143 offset:51200
	ds_read_b128 v[176:179], v143 offset:52224
	ds_read_b128 v[180:183], v143 offset:53248
	ds_read_b128 v[184:187], v143 offset:54272
	ds_read_b128 v[188:191], v143 offset:55296
	ds_read_b128 v[192:195], v143 offset:56320
	global_load_lds_dwordx4 v[140:141], off
	v_lshl_add_u64 v[140:141], v[218:219], 0, s[0:1]
	s_mov_b32 m0, s21
	s_nop 0
	global_load_lds_dwordx4 v[140:141], off
	s_barrier
; DI float silu_f(float g) { return g * __builtin_amdgcn_rcpf(1.f + __builtin_amdgcn_exp2f(-LOG2E * g)); }
; #define WAIT_V(n) asm volatile("s_waitcnt vmcnt(" #n ")" ::: "memory")
; #define WAIT_L(n) asm volatile("s_waitcnt lgkmcnt(" #n ")" ::: "memory")
; #define BAR __builtin_amdgcn_s_barrier()
; #define SCHED __builtin_amdgcn_sched_barrier(0)
; template <class Get, class Epi>
; DI void gemm_stream(LAS unsigned char* lds, const int K, const int ld, Get get, Epi epi) {
;     ...
;             BAR; WAIT_L(0); MMA(1, 0, At, B0); BAR; SCHED;
;             STAGE(SBo(1, 1), b3 + hstep);
;             WAIT_V(6); BAR; MMA(1, 1, At, B1); BAR;
;         }
; DI void epi_swiglu(const Acc& acc, int brow, int pn, bf16_t* hid) {
;     ...
;     for (int ai = 0; ai < 2; ++ai)
; #pragma unroll
;         for (int m = 0; m < 4; ++m) {
;             const int r = brow + ai * 128 + wr * 64 + m * 16 + fr;
;             bf16_t* rp = hid + (size_t)r * FF + pn * 128 + wc * 32 + fq * 4;
; #pragma unroll
;             for (int n = 0; n < 2; ++n) {
;                 const f32x4 g = acc[ai][0][m][n], u = acc[ai][1][m][n];
;                 float o[4];
; #pragma unroll
;                 for (int j = 0; j < 4; ++j) o[j] = silu_f(g[j]) * u[j];
;                 st4(rp + n * 16, o[0], o[1], o[2], o[3]);
;             }
	s_waitcnt lgkmcnt(0)
	v_mfma_f32_16x16x32_bf16 v[60:63], v[148:151], v[164:167], v[60:63]
	v_mfma_f32_16x16x32_bf16 v[52:55], v[156:159], v[164:167], v[52:55]
	v_mfma_f32_16x16x32_bf16 v[44:47], v[148:151], v[172:175], v[44:47]
	v_mfma_f32_16x16x32_bf16 v[36:39], v[156:159], v[172:175], v[36:39]
	v_mfma_f32_16x16x32_bf16 v[28:31], v[148:151], v[180:183], v[28:31]
	v_mfma_f32_16x16x32_bf16 v[20:23], v[156:159], v[180:183], v[20:23]
	v_mfma_f32_16x16x32_bf16 v[12:15], v[148:151], v[188:191], v[12:15]
	v_mfma_f32_16x16x32_bf16 v[4:7], v[156:159], v[188:191], v[4:7]
	v_mfma_f32_16x16x32_bf16 v[60:63], v[152:155], v[168:171], v[60:63]
	v_mfma_f32_16x16x32_bf16 v[52:55], v[160:163], v[168:171], v[52:55]
	v_mfma_f32_16x16x32_bf16 v[44:47], v[152:155], v[176:179], v[44:47]
	v_mfma_f32_16x16x32_bf16 v[36:39], v[160:163], v[176:179], v[36:39]
	v_mfma_f32_16x16x32_bf16 v[28:31], v[152:155], v[184:187], v[28:31]
	v_mfma_f32_16x16x32_bf16 v[20:23], v[160:163], v[184:187], v[20:23]
	v_mfma_f32_16x16x32_bf16 v[12:15], v[152:155], v[192:195], v[12:15]
	v_mfma_f32_16x16x32_bf16 v[4:7], v[160:163], v[192:195], v[4:7]
	s_barrier
	s_add_u32 s12, s12, 0x80080
	s_addc_u32 s13, s13, 0
	s_mov_b32 m0, s41
	v_lshl_add_u64 v[140:141], s[12:13], 0, v[130:131]
	global_load_lds_dwordx4 v[140:141], off
	v_lshl_add_u64 v[140:141], s[12:13], 0, v[128:129]
	s_mov_b32 m0, s52
	s_nop 0
	global_load_lds_dwordx4 v[140:141], off
	s_add_i32 s59, s59, 2
	s_add_u32 s10, s10, 0x100
	s_addc_u32 s11, s11, 0
	s_add_u32 s57, s57, 0x100
	s_addc_u32 s58, s58, 0
	s_cmp_gt_u32 s59, 29
	s_waitcnt vmcnt(6)
	s_barrier
	v_mfma_f32_16x16x32_bf16 v[56:59], v[196:199], v[164:167], v[56:59]
	v_mfma_f32_16x16x32_bf16 v[48:51], v[208:211], v[164:167], v[48:51]
	v_mfma_f32_16x16x32_bf16 v[40:43], v[196:199], v[172:175], v[40:43]
	v_mfma_f32_16x16x32_bf16 v[32:35], v[208:211], v[172:175], v[32:35]
	v_mfma_f32_16x16x32_bf16 v[24:27], v[196:199], v[180:183], v[24:27]
	v_mfma_f32_16x16x32_bf16 v[16:19], v[208:211], v[180:183], v[16:19]
	v_mfma_f32_16x16x32_bf16 v[8:11], v[196:199], v[188:191], v[8:11]
	v_mfma_f32_16x16x32_bf16 v[0:3], v[208:211], v[188:191], v[0:3]
	v_mfma_f32_16x16x32_bf16 v[56:59], v[200:203], v[168:171], v[56:59]
	v_mfma_f32_16x16x32_bf16 v[48:51], v[212:215], v[168:171], v[48:51]
	v_mfma_f32_16x16x32_bf16 v[40:43], v[200:203], v[176:179], v[40:43]
	v_mfma_f32_16x16x32_bf16 v[32:35], v[212:215], v[176:179], v[32:35]
	v_mfma_f32_16x16x32_bf16 v[24:27], v[200:203], v[184:187], v[24:27]
	v_mfma_f32_16x16x32_bf16 v[16:19], v[212:215], v[184:187], v[16:19]
	v_mfma_f32_16x16x32_bf16 v[8:11], v[200:203], v[192:195], v[8:11]
	v_mfma_f32_16x16x32_bf16 v[0:3], v[212:215], v[192:195], v[0:3]
	s_barrier
	s_cbranch_scc0 .LBB0_1630
	s_lshl_b32 s10, s55, 8
	v_mov_b32_e32 v132, v206
	v_mul_f32_e32 v149, 0xbfb8aa3b, v125
	v_and_or_b32 v141, v132, 15, s10
	s_lshl_b32 s10, s56, 7
	s_ashr_i32 s11, s10, 31
	s_lshl_b64 s[10:11], s[10:11], 1
	v_ashrrev_i32_e32 v140, 2, v132
	s_add_u32 s10, s80, s10
	v_and_b32_e32 v140, 0xffffffc0, v140
	s_addc_u32 s11, s81, s11
	v_lshrrev_b32_e32 v148, 1, v132
	v_and_b32_e32 v132, 0xc0, v132
	v_add_u32_e32 v147, v141, v140
	v_lshl_add_u64 v[140:141], s[10:11], 0, v[132:133]
	v_and_b32_e32 v132, 24, v148
	v_mul_f32_e32 v148, 0xbfb8aa3b, v124
	v_exp_f32_e32 v148, v148
	v_exp_f32_e32 v149, v149
	v_lshl_add_u64 v[140:141], v[140:141], 0, v[132:133]
	v_mad_i64_i32 v[152:153], s[10:11], v147, s23, v[140:141]
	v_add_f32_e32 v132, 1.0, v148
	v_rcp_f32_e32 v148, v132
	v_add_f32_e32 v132, 1.0, v149
	v_mul_f32_e32 v149, 0xbfb8aa3b, v126
	v_exp_f32_e32 v150, v149
	v_mul_f32_e32 v149, 0xbfb8aa3b, v127
	v_exp_f32_e32 v151, v149
	v_rcp_f32_e32 v149, v132
	v_add_f32_e32 v132, 1.0, v150
	v_rcp_f32_e32 v150, v132
	v_add_f32_e32 v132, 1.0, v151
	v_rcp_f32_e32 v151, v132
	v_pk_mul_f32 v[124:125], v[124:125], v[148:149]
	s_and_b64 vcc, exec, s[4:5]
	v_pk_mul_f32 v[120:121], v[124:125], v[120:121]
	v_pk_mul_f32 v[124:125], v[126:127], v[150:151]
	v_cvt_pk_bf16_f32 v120, v120, v121
	v_mul_f32_e32 v121, 0xbfb8aa3b, v116
	v_pk_mul_f32 v[122:123], v[124:125], v[122:123]
	v_exp_f32_e32 v124, v121
	v_mul_f32_e32 v121, 0xbfb8aa3b, v117
	v_exp_f32_e32 v125, v121
	v_cvt_pk_bf16_f32 v121, v122, v123
	v_add_f32_e32 v122, 1.0, v124
	v_mul_f32_e32 v124, 0xbfb8aa3b, v118
	v_add_f32_e32 v123, 1.0, v125
	v_mul_f32_e32 v125, 0xbfb8aa3b, v119
	v_exp_f32_e32 v124, v124
	v_exp_f32_e32 v125, v125
	v_rcp_f32_e32 v122, v122
	v_rcp_f32_e32 v123, v123
	v_add_f32_e32 v124, 1.0, v124
	v_add_f32_e32 v125, 1.0, v125
	v_rcp_f32_e32 v124, v124
	v_rcp_f32_e32 v125, v125
	v_pk_mul_f32 v[116:117], v[116:117], v[122:123]
	s_mov_b32 s56, s53
	v_pk_mul_f32 v[112:113], v[116:117], v[112:113]
	v_pk_mul_f32 v[116:117], v[118:119], v[124:125]
	v_cvt_pk_bf16_f32 v112, v112, v113
	v_pk_mul_f32 v[114:115], v[116:117], v[114:115]
	v_or_b32_e32 v116, 16, v147
	v_cvt_pk_bf16_f32 v113, v114, v115
	global_store_dwordx2 v[152:153], v[112:113], off offset:32
	v_mul_f32_e32 v112, 0xbfb8aa3b, v108
	v_mul_f32_e32 v113, 0xbfb8aa3b, v109
	v_exp_f32_e32 v112, v112
	v_exp_f32_e32 v113, v113
	v_mul_f32_e32 v114, 0xbfb8aa3b, v110
	v_mul_f32_e32 v115, 0xbfb8aa3b, v111
	v_exp_f32_e32 v114, v114
	v_exp_f32_e32 v115, v115
	v_add_f32_e32 v112, 1.0, v112
	v_add_f32_e32 v113, 1.0, v113
	v_rcp_f32_e32 v112, v112
	v_rcp_f32_e32 v113, v113
	v_add_f32_e32 v114, 1.0, v114
	v_add_f32_e32 v115, 1.0, v115
	v_rcp_f32_e32 v114, v114
	v_rcp_f32_e32 v115, v115
	v_pk_mul_f32 v[108:109], v[108:109], v[112:113]
	v_mad_i64_i32 v[116:117], s[10:11], v116, s23, v[140:141]
	v_pk_mul_f32 v[104:105], v[108:109], v[104:105]
	v_pk_mul_f32 v[108:109], v[110:111], v[114:115]
; DI float silu_f(float g) { return g * __builtin_amdgcn_rcpf(1.f + __builtin_amdgcn_exp2f(-LOG2E * g)); }
; DI void epi_swiglu(const Acc& acc, int brow, int pn, bf16_t* hid) {
;     ...
;     for (int ai = 0; ai < 2; ++ai)
; #pragma unroll
;         for (int m = 0; m < 4; ++m) {
;             const int r = brow + ai * 128 + wr * 64 + m * 16 + fr;
;             bf16_t* rp = hid + (size_t)r * FF + pn * 128 + wc * 32 + fq * 4;
; #pragma unroll
;             for (int n = 0; n < 2; ++n) {
;                 const f32x4 g = acc[ai][0][m][n], u = acc[ai][1][m][n];
;                 float o[4];
; #pragma unroll
;                 for (int j = 0; j < 4; ++j) o[j] = silu_f(g[j]) * u[j];
;                 st4(rp + n * 16, o[0], o[1], o[2], o[3]);
;             }
	v_cvt_pk_bf16_f32 v104, v104, v105
	v_mul_f32_e32 v105, 0xbfb8aa3b, v100
	v_pk_mul_f32 v[106:107], v[108:109], v[106:107]
	v_exp_f32_e32 v108, v105
	v_mul_f32_e32 v105, 0xbfb8aa3b, v101
	v_exp_f32_e32 v109, v105
	v_cvt_pk_bf16_f32 v105, v106, v107
	v_add_f32_e32 v106, 1.0, v108
	v_mul_f32_e32 v108, 0xbfb8aa3b, v102
	v_add_f32_e32 v107, 1.0, v109
	v_mul_f32_e32 v109, 0xbfb8aa3b, v103
	v_exp_f32_e32 v108, v108
	v_exp_f32_e32 v109, v109
	v_rcp_f32_e32 v106, v106
	v_rcp_f32_e32 v107, v107
	v_add_f32_e32 v108, 1.0, v108
	v_add_f32_e32 v109, 1.0, v109
	v_rcp_f32_e32 v108, v108
	v_rcp_f32_e32 v109, v109
	v_pk_mul_f32 v[100:101], v[100:101], v[106:107]
	s_mov_b32 s55, s54
	v_pk_mul_f32 v[96:97], v[100:101], v[96:97]
	v_pk_mul_f32 v[100:101], v[102:103], v[108:109]
	v_cvt_pk_bf16_f32 v96, v96, v97
	v_pk_mul_f32 v[98:99], v[100:101], v[98:99]
	v_or_b32_e32 v100, 32, v147
	v_cvt_pk_bf16_f32 v97, v98, v99
	global_store_dwordx2 v[116:117], v[96:97], off offset:32
	v_mul_f32_e32 v96, 0xbfb8aa3b, v92
	v_mul_f32_e32 v97, 0xbfb8aa3b, v93
	v_exp_f32_e32 v96, v96
	v_exp_f32_e32 v97, v97
	v_mul_f32_e32 v98, 0xbfb8aa3b, v94
	v_mul_f32_e32 v99, 0xbfb8aa3b, v95
	v_exp_f32_e32 v98, v98
	v_exp_f32_e32 v99, v99
	v_add_f32_e32 v96, 1.0, v96
	v_add_f32_e32 v97, 1.0, v97
	v_rcp_f32_e32 v96, v96
	v_rcp_f32_e32 v97, v97
	v_add_f32_e32 v98, 1.0, v98
	v_add_f32_e32 v99, 1.0, v99
	v_rcp_f32_e32 v98, v98
	v_rcp_f32_e32 v99, v99
	v_pk_mul_f32 v[92:93], v[92:93], v[96:97]
	v_mad_i64_i32 v[100:101], s[10:11], v100, s23, v[140:141]
	v_pk_mul_f32 v[88:89], v[92:93], v[88:89]
	v_pk_mul_f32 v[92:93], v[94:95], v[98:99]
	v_cvt_pk_bf16_f32 v88, v88, v89
	v_mul_f32_e32 v89, 0xbfb8aa3b, v84
	v_pk_mul_f32 v[90:91], v[92:93], v[90:91]
	v_exp_f32_e32 v92, v89
	v_mul_f32_e32 v89, 0xbfb8aa3b, v85
	v_exp_f32_e32 v93, v89
	v_cvt_pk_bf16_f32 v89, v90, v91
	v_add_f32_e32 v90, 1.0, v92
	v_mul_f32_e32 v92, 0xbfb8aa3b, v86
	v_add_f32_e32 v91, 1.0, v93
	v_mul_f32_e32 v93, 0xbfb8aa3b, v87
	v_exp_f32_e32 v92, v92
	v_exp_f32_e32 v93, v93
	v_rcp_f32_e32 v90, v90
	v_rcp_f32_e32 v91, v91
	v_add_f32_e32 v92, 1.0, v92
	v_add_f32_e32 v93, 1.0, v93
	v_rcp_f32_e32 v92, v92
	v_rcp_f32_e32 v93, v93
	v_pk_mul_f32 v[84:85], v[84:85], v[90:91]
	s_mov_b64 s[12:13], s[8:9]
	v_pk_mul_f32 v[80:81], v[84:85], v[80:81]
	v_pk_mul_f32 v[84:85], v[86:87], v[92:93]
	v_cvt_pk_bf16_f32 v80, v80, v81
	v_pk_mul_f32 v[82:83], v[84:85], v[82:83]
	v_or_b32_e32 v84, 48, v147
	v_cvt_pk_bf16_f32 v81, v82, v83
	global_store_dwordx2 v[100:101], v[80:81], off offset:32
	v_mul_f32_e32 v80, 0xbfb8aa3b, v76
	v_mul_f32_e32 v81, 0xbfb8aa3b, v77
	v_exp_f32_e32 v80, v80
	v_exp_f32_e32 v81, v81
	v_mul_f32_e32 v82, 0xbfb8aa3b, v78
	v_mul_f32_e32 v83, 0xbfb8aa3b, v79
	v_exp_f32_e32 v82, v82
	v_exp_f32_e32 v83, v83
	v_add_f32_e32 v80, 1.0, v80
	v_add_f32_e32 v81, 1.0, v81
	v_rcp_f32_e32 v80, v80
	v_rcp_f32_e32 v81, v81
	v_add_f32_e32 v82, 1.0, v82
	v_add_f32_e32 v83, 1.0, v83
	v_rcp_f32_e32 v82, v82
	v_rcp_f32_e32 v83, v83
	v_pk_mul_f32 v[76:77], v[76:77], v[80:81]
	v_mad_i64_i32 v[84:85], s[10:11], v84, s23, v[140:141]
	v_pk_mul_f32 v[72:73], v[76:77], v[72:73]
	v_pk_mul_f32 v[76:77], v[78:79], v[82:83]
	v_cvt_pk_bf16_f32 v72, v72, v73
	v_mul_f32_e32 v73, 0xbfb8aa3b, v68
	v_pk_mul_f32 v[74:75], v[76:77], v[74:75]
	v_exp_f32_e32 v76, v73
	v_mul_f32_e32 v73, 0xbfb8aa3b, v69
	v_exp_f32_e32 v77, v73
	v_cvt_pk_bf16_f32 v73, v74, v75
	v_add_f32_e32 v74, 1.0, v76
	v_mul_f32_e32 v76, 0xbfb8aa3b, v70
	v_add_f32_e32 v75, 1.0, v77
	v_mul_f32_e32 v77, 0xbfb8aa3b, v71
	v_exp_f32_e32 v76, v76
	v_exp_f32_e32 v77, v77
	v_rcp_f32_e32 v74, v74
	v_rcp_f32_e32 v75, v75
	v_add_f32_e32 v76, 1.0, v76
	v_add_f32_e32 v77, 1.0, v77
	v_rcp_f32_e32 v76, v76
	v_rcp_f32_e32 v77, v77
	v_pk_mul_f32 v[68:69], v[68:69], v[74:75]
	global_store_dwordx2 v[152:153], v[120:121], off
	v_pk_mul_f32 v[64:65], v[68:69], v[64:65]
	v_pk_mul_f32 v[68:69], v[70:71], v[76:77]
	v_cvt_pk_bf16_f32 v64, v64, v65
	v_pk_mul_f32 v[66:67], v[68:69], v[66:67]
	v_add_u32_e32 v68, 0x80, v147
	v_cvt_pk_bf16_f32 v65, v66, v67
	global_store_dwordx2 v[84:85], v[64:65], off offset:32
	v_mul_f32_e32 v64, 0xbfb8aa3b, v60
	v_mul_f32_e32 v65, 0xbfb8aa3b, v61
	v_exp_f32_e32 v64, v64
	v_exp_f32_e32 v65, v65
	v_mul_f32_e32 v66, 0xbfb8aa3b, v62
	v_mul_f32_e32 v67, 0xbfb8aa3b, v63
	v_exp_f32_e32 v66, v66
	v_exp_f32_e32 v67, v67
	v_add_f32_e32 v64, 1.0, v64
	v_add_f32_e32 v65, 1.0, v65
	v_rcp_f32_e32 v64, v64
	v_rcp_f32_e32 v65, v65
	v_add_f32_e32 v66, 1.0, v66
	v_add_f32_e32 v67, 1.0, v67
	v_rcp_f32_e32 v66, v66
	v_rcp_f32_e32 v67, v67
	v_pk_mul_f32 v[60:61], v[60:61], v[64:65]
	v_mad_i64_i32 v[68:69], s[10:11], v68, s23, v[140:141]
	v_pk_mul_f32 v[56:57], v[60:61], v[56:57]
	v_pk_mul_f32 v[60:61], v[62:63], v[66:67]
	v_cvt_pk_bf16_f32 v56, v56, v57
	v_mul_f32_e32 v57, 0xbfb8aa3b, v52
	v_pk_mul_f32 v[58:59], v[60:61], v[58:59]
	v_exp_f32_e32 v60, v57
	v_mul_f32_e32 v57, 0xbfb8aa3b, v53
	v_exp_f32_e32 v61, v57
	v_cvt_pk_bf16_f32 v57, v58, v59
	v_add_f32_e32 v58, 1.0, v60
	v_mul_f32_e32 v60, 0xbfb8aa3b, v54
	v_add_f32_e32 v59, 1.0, v61
	v_mul_f32_e32 v61, 0xbfb8aa3b, v55
	v_exp_f32_e32 v60, v60
	v_exp_f32_e32 v61, v61
	v_rcp_f32_e32 v58, v58
	v_rcp_f32_e32 v59, v59
	v_add_f32_e32 v60, 1.0, v60
	v_add_f32_e32 v61, 1.0, v61
	v_rcp_f32_e32 v60, v60
	v_rcp_f32_e32 v61, v61
; DI float silu_f(float g) { return g * __builtin_amdgcn_rcpf(1.f + __builtin_amdgcn_exp2f(-LOG2E * g)); }
; #define WAIT_V(n) asm volatile("s_waitcnt vmcnt(" #n ")" ::: "memory")
; #define BAR __builtin_amdgcn_s_barrier()
; template <class Get, class Epi>
; DI void gemm_stream(LAS unsigned char* lds, const int K, const int ld, Get get, Epi epi) {
;     ...
;         epi(acc, cur);
;         if (!has_next) break;
;         ZERO_ACC;
;         cur = nxt; cA = nA; cB = nB; ++ui;
;     }
;     WAIT_V(0);
;     if (wr == 0) BAR;
;     BAR;
; DI void epi_swiglu(const Acc& acc, int brow, int pn, bf16_t* hid) {
;     ...
;     for (int ai = 0; ai < 2; ++ai)
; #pragma unroll
;         for (int m = 0; m < 4; ++m) {
;             const int r = brow + ai * 128 + wr * 64 + m * 16 + fr;
;             bf16_t* rp = hid + (size_t)r * FF + pn * 128 + wc * 32 + fq * 4;
; #pragma unroll
;             for (int n = 0; n < 2; ++n) {
;                 const f32x4 g = acc[ai][0][m][n], u = acc[ai][1][m][n];
;                 float o[4];
; #pragma unroll
;                 for (int j = 0; j < 4; ++j) o[j] = silu_f(g[j]) * u[j];
;                 st4(rp + n * 16, o[0], o[1], o[2], o[3]);
;             }
	v_pk_mul_f32 v[52:53], v[52:53], v[58:59]
	global_store_dwordx2 v[116:117], v[104:105], off
	v_pk_mul_f32 v[48:49], v[52:53], v[48:49]
	v_pk_mul_f32 v[52:53], v[54:55], v[60:61]
	v_cvt_pk_bf16_f32 v48, v48, v49
	v_pk_mul_f32 v[50:51], v[52:53], v[50:51]
	v_add_u32_e32 v52, 0x90, v147
	v_cvt_pk_bf16_f32 v49, v50, v51
	global_store_dwordx2 v[68:69], v[48:49], off offset:32
	v_mul_f32_e32 v48, 0xbfb8aa3b, v44
	v_mul_f32_e32 v49, 0xbfb8aa3b, v45
	v_exp_f32_e32 v48, v48
	v_exp_f32_e32 v49, v49
	v_mul_f32_e32 v50, 0xbfb8aa3b, v46
	v_mul_f32_e32 v51, 0xbfb8aa3b, v47
	v_exp_f32_e32 v50, v50
	v_exp_f32_e32 v51, v51
	v_add_f32_e32 v48, 1.0, v48
	v_add_f32_e32 v49, 1.0, v49
	v_rcp_f32_e32 v48, v48
	v_rcp_f32_e32 v49, v49
	v_add_f32_e32 v50, 1.0, v50
	v_add_f32_e32 v51, 1.0, v51
	v_rcp_f32_e32 v50, v50
	v_rcp_f32_e32 v51, v51
	v_pk_mul_f32 v[44:45], v[44:45], v[48:49]
	v_mad_i64_i32 v[52:53], s[10:11], v52, s23, v[140:141]
	v_pk_mul_f32 v[40:41], v[44:45], v[40:41]
	v_pk_mul_f32 v[44:45], v[46:47], v[50:51]
	v_cvt_pk_bf16_f32 v40, v40, v41
	v_mul_f32_e32 v41, 0xbfb8aa3b, v36
	v_pk_mul_f32 v[42:43], v[44:45], v[42:43]
	v_exp_f32_e32 v44, v41
	v_mul_f32_e32 v41, 0xbfb8aa3b, v37
	v_exp_f32_e32 v45, v41
	v_cvt_pk_bf16_f32 v41, v42, v43
	v_add_f32_e32 v42, 1.0, v44
	v_mul_f32_e32 v44, 0xbfb8aa3b, v38
	v_add_f32_e32 v43, 1.0, v45
	v_mul_f32_e32 v45, 0xbfb8aa3b, v39
	v_exp_f32_e32 v44, v44
	v_exp_f32_e32 v45, v45
	v_rcp_f32_e32 v42, v42
	v_rcp_f32_e32 v43, v43
	v_add_f32_e32 v44, 1.0, v44
	v_add_f32_e32 v45, 1.0, v45
	v_rcp_f32_e32 v44, v44
	v_rcp_f32_e32 v45, v45
	v_pk_mul_f32 v[36:37], v[36:37], v[42:43]
	global_store_dwordx2 v[100:101], v[88:89], off
	v_pk_mul_f32 v[32:33], v[36:37], v[32:33]
	v_pk_mul_f32 v[36:37], v[38:39], v[44:45]
	v_cvt_pk_bf16_f32 v32, v32, v33
	v_pk_mul_f32 v[34:35], v[36:37], v[34:35]
	v_add_u32_e32 v36, 0xa0, v147
	v_cvt_pk_bf16_f32 v33, v34, v35
	global_store_dwordx2 v[52:53], v[32:33], off offset:32
	v_mul_f32_e32 v32, 0xbfb8aa3b, v28
	v_mul_f32_e32 v33, 0xbfb8aa3b, v29
	v_exp_f32_e32 v32, v32
	v_exp_f32_e32 v33, v33
	v_mul_f32_e32 v34, 0xbfb8aa3b, v30
	v_mul_f32_e32 v35, 0xbfb8aa3b, v31
	v_exp_f32_e32 v34, v34
	v_exp_f32_e32 v35, v35
	v_add_f32_e32 v32, 1.0, v32
	v_add_f32_e32 v33, 1.0, v33
	v_rcp_f32_e32 v32, v32
	v_rcp_f32_e32 v33, v33
	v_add_f32_e32 v34, 1.0, v34
	v_add_f32_e32 v35, 1.0, v35
	v_rcp_f32_e32 v34, v34
	v_rcp_f32_e32 v35, v35
	v_pk_mul_f32 v[28:29], v[28:29], v[32:33]
	v_mad_i64_i32 v[36:37], s[10:11], v36, s23, v[140:141]
	v_pk_mul_f32 v[24:25], v[28:29], v[24:25]
	v_pk_mul_f32 v[28:29], v[30:31], v[34:35]
	v_cvt_pk_bf16_f32 v24, v24, v25
	v_mul_f32_e32 v25, 0xbfb8aa3b, v20
	v_pk_mul_f32 v[26:27], v[28:29], v[26:27]
	v_exp_f32_e32 v28, v25
	v_mul_f32_e32 v25, 0xbfb8aa3b, v21
	v_exp_f32_e32 v29, v25
	v_cvt_pk_bf16_f32 v25, v26, v27
	v_add_f32_e32 v26, 1.0, v28
	v_mul_f32_e32 v28, 0xbfb8aa3b, v22
	v_add_f32_e32 v27, 1.0, v29
	v_mul_f32_e32 v29, 0xbfb8aa3b, v23
	v_exp_f32_e32 v28, v28
	v_exp_f32_e32 v29, v29
	v_rcp_f32_e32 v26, v26
	v_rcp_f32_e32 v27, v27
	v_add_f32_e32 v28, 1.0, v28
	v_add_f32_e32 v29, 1.0, v29
	v_rcp_f32_e32 v28, v28
	v_rcp_f32_e32 v29, v29
	v_pk_mul_f32 v[20:21], v[20:21], v[26:27]
	global_store_dwordx2 v[84:85], v[72:73], off
	v_pk_mul_f32 v[16:17], v[20:21], v[16:17]
	v_pk_mul_f32 v[20:21], v[22:23], v[28:29]
	v_cvt_pk_bf16_f32 v16, v16, v17
	v_pk_mul_f32 v[18:19], v[20:21], v[18:19]
	v_add_u32_e32 v20, 0xb0, v147
	v_cvt_pk_bf16_f32 v17, v18, v19
	global_store_dwordx2 v[36:37], v[16:17], off offset:32
	v_mul_f32_e32 v16, 0xbfb8aa3b, v12
	v_mul_f32_e32 v17, 0xbfb8aa3b, v13
	v_exp_f32_e32 v16, v16
	v_exp_f32_e32 v17, v17
	v_mul_f32_e32 v18, 0xbfb8aa3b, v14
	v_mul_f32_e32 v19, 0xbfb8aa3b, v15
	v_exp_f32_e32 v18, v18
	v_exp_f32_e32 v19, v19
	v_add_f32_e32 v16, 1.0, v16
	v_add_f32_e32 v17, 1.0, v17
	v_rcp_f32_e32 v16, v16
	v_rcp_f32_e32 v17, v17
	v_add_f32_e32 v18, 1.0, v18
	v_add_f32_e32 v19, 1.0, v19
	v_rcp_f32_e32 v18, v18
	v_rcp_f32_e32 v19, v19
	v_pk_mul_f32 v[12:13], v[12:13], v[16:17]
	v_mad_i64_i32 v[20:21], s[10:11], v20, s23, v[140:141]
	v_pk_mul_f32 v[8:9], v[12:13], v[8:9]
	v_pk_mul_f32 v[12:13], v[14:15], v[18:19]
	v_cvt_pk_bf16_f32 v8, v8, v9
	v_mul_f32_e32 v9, 0xbfb8aa3b, v4
	v_pk_mul_f32 v[10:11], v[12:13], v[10:11]
	v_exp_f32_e32 v12, v9
	v_mul_f32_e32 v9, 0xbfb8aa3b, v5
	v_exp_f32_e32 v13, v9
	v_cvt_pk_bf16_f32 v9, v10, v11
	v_add_f32_e32 v10, 1.0, v12
	v_mul_f32_e32 v12, 0xbfb8aa3b, v6
	v_add_f32_e32 v11, 1.0, v13
	v_mul_f32_e32 v13, 0xbfb8aa3b, v7
	v_exp_f32_e32 v12, v12
	v_exp_f32_e32 v13, v13
	v_rcp_f32_e32 v10, v10
	v_rcp_f32_e32 v11, v11
	v_add_f32_e32 v12, 1.0, v12
	v_add_f32_e32 v13, 1.0, v13
	v_rcp_f32_e32 v12, v12
	v_rcp_f32_e32 v13, v13
	v_pk_mul_f32 v[4:5], v[4:5], v[10:11]
	s_mov_b64 s[10:11], s[6:7]
	v_pk_mul_f32 v[0:1], v[4:5], v[0:1]
	v_pk_mul_f32 v[4:5], v[6:7], v[12:13]
	v_cvt_pk_bf16_f32 v0, v0, v1
	v_pk_mul_f32 v[2:3], v[4:5], v[2:3]
	global_store_dwordx2 v[68:69], v[56:57], off
	v_cvt_pk_bf16_f32 v1, v2, v3
	global_store_dwordx2 v[52:53], v[40:41], off
	global_store_dwordx2 v[36:37], v[24:25], off
	global_store_dwordx2 v[20:21], v[8:9], off
	global_store_dwordx2 v[20:21], v[0:1], off offset:32
	s_cbranch_vccz .LBB0_1627
	s_waitcnt vmcnt(0)
	s_cmpk_gt_u32 s2, 0xff
	s_cbranch_scc1 .LBB0_1634
	s_barrier

; #define WAIT_V(n) asm volatile("s_waitcnt vmcnt(" #n ")" ::: "memory")
; #define WAIT_L(n) asm volatile("s_waitcnt lgkmcnt(" #n ")" ::: "memory")
; #define BAR __builtin_amdgcn_s_barrier()
; #define SCHED __builtin_amdgcn_sched_barrier(0)
; template <class Get, class Epi>
; DI void gemm_stream(LAS unsigned char* lds, const int K, const int ld, Get get, Epi epi) {
;     ...
;             const bool last = (t == nt - 2);
;             const char* a1 = cA + (size_t)(t + 1) * kstep;
;             const char* a2 = last ? nA : cA + (size_t)(t + 2) * kstep;
;             const char* b2 = last ? nB : cB + (size_t)(t + 2) * kstep;
;             const char* a3 = a2 + kstep;
;             const char* b3 = b2 + kstep;
;             LDB(B0, 0, 0); SCHED; LDA(At, 0, 0); STAGE(SAo(1, 1), a1 + hstep);
;             WAIT_L(8); BAR; WAIT_L(0); MMA(0, 0, At, B0); BAR; SCHED;
;             LDB(B1, 0, 1); STAGE(SBo(0, 0), b2);
;             BAR; WAIT_L(0); MMA(0, 1, At, B1); BAR;
;             LDA(At, 0, 1); STAGE(SAo(0, 0), a2);
;             BAR; WAIT_L(0); MMA(1, 0, At, B0); BAR; SCHED;
;             STAGE(SBo(0, 1), b2 + hstep);
;             WAIT_V(6); BAR; MMA(1, 1, At, B1); BAR;
.LBB0_2670:
	ds_read_b128 v[128:131], v198
	ds_read_b128 v[132:135], v198 offset:1024
	ds_read_b128 v[136:139], v198 offset:2048
	ds_read_b128 v[140:143], v198 offset:3072
	s_mov_b32 m0, s52
	v_lshl_add_u64 v[186:187], s[6:7], 0, v[168:169]
	ds_read_b128 v[144:147], v199
	ds_read_b128 v[148:151], v199 offset:1024
	ds_read_b128 v[152:155], v199 offset:2048
	ds_read_b128 v[156:159], v199 offset:3072
	ds_read_b128 v[160:163], v199 offset:4096
	ds_read_b128 v[174:177], v199 offset:5120
	ds_read_b128 v[178:181], v199 offset:6144
	ds_read_b128 v[182:185], v199 offset:7168
	global_load_lds_dwordx4 v[186:187], off
	v_lshl_add_u64 v[186:187], s[6:7], 0, v[170:171]
	s_mov_b32 m0, s53
	s_nop 0
	global_load_lds_dwordx4 v[186:187], off
	s_waitcnt lgkmcnt(8)
	s_barrier
	s_waitcnt lgkmcnt(0)
	v_mfma_f32_16x16x32_bf16 v[124:127], v[128:131], v[144:147], v[124:127]
	v_mfma_f32_16x16x32_bf16 v[92:95], v[136:139], v[144:147], v[92:95]
	v_mfma_f32_16x16x32_bf16 v[120:123], v[128:131], v[152:155], v[120:123]
	v_mfma_f32_16x16x32_bf16 v[88:91], v[136:139], v[152:155], v[88:91]
	v_mfma_f32_16x16x32_bf16 v[116:119], v[128:131], v[160:163], v[116:119]
	v_mfma_f32_16x16x32_bf16 v[84:87], v[136:139], v[160:163], v[84:87]
	v_mfma_f32_16x16x32_bf16 v[112:115], v[128:131], v[178:181], v[112:115]
	v_mfma_f32_16x16x32_bf16 v[80:83], v[136:139], v[178:181], v[80:83]
	v_mfma_f32_16x16x32_bf16 v[124:127], v[132:135], v[148:151], v[124:127]
	v_mfma_f32_16x16x32_bf16 v[92:95], v[140:143], v[148:151], v[92:95]
	v_mfma_f32_16x16x32_bf16 v[120:123], v[132:135], v[156:159], v[120:123]
	v_mfma_f32_16x16x32_bf16 v[88:91], v[140:143], v[156:159], v[88:91]
	v_mfma_f32_16x16x32_bf16 v[116:119], v[132:135], v[174:177], v[116:119]
	v_mfma_f32_16x16x32_bf16 v[84:87], v[140:143], v[174:177], v[84:87]
	v_mfma_f32_16x16x32_bf16 v[112:115], v[132:135], v[182:185], v[112:115]
	v_mfma_f32_16x16x32_bf16 v[80:83], v[140:143], v[182:185], v[80:83]
	s_barrier
	s_add_u32 s8, s6, 0x100
	s_addc_u32 s9, s7, 0
	s_cmp_eq_u32 s16, 60
	s_cselect_b32 s13, s39, s9
	s_cselect_b32 s12, s38, s8
	s_cselect_b32 s11, s41, s15
	s_cselect_b32 s10, s40, s14
	s_mov_b32 m0, s58
	v_lshl_add_u64 v[204:205], s[10:11], 0, v[164:165]
	ds_read_b128 v[186:189], v200
	ds_read_b128 v[190:193], v200 offset:1024
	ds_read_b128 v[194:197], v200 offset:2048
	ds_read_b128 v[208:211], v200 offset:3072
	global_load_lds_dwordx4 v[204:205], off
	v_lshl_add_u64 v[212:213], s[10:11], 0, v[166:167]
	s_mov_b32 m0, s59
	s_nop 0
	global_load_lds_dwordx4 v[212:213], off
	s_barrier
	s_waitcnt lgkmcnt(0)
	v_mfma_f32_16x16x32_bf16 v[60:63], v[186:189], v[144:147], v[60:63]
	v_mfma_f32_16x16x32_bf16 v[28:31], v[194:197], v[144:147], v[28:31]
	v_mfma_f32_16x16x32_bf16 v[56:59], v[186:189], v[152:155], v[56:59]
	v_mfma_f32_16x16x32_bf16 v[24:27], v[194:197], v[152:155], v[24:27]
	v_mfma_f32_16x16x32_bf16 v[52:55], v[186:189], v[160:163], v[52:55]
	v_mfma_f32_16x16x32_bf16 v[20:23], v[194:197], v[160:163], v[20:23]
	v_mfma_f32_16x16x32_bf16 v[48:51], v[186:189], v[178:181], v[48:51]
	v_mfma_f32_16x16x32_bf16 v[16:19], v[194:197], v[178:181], v[16:19]
	v_mfma_f32_16x16x32_bf16 v[60:63], v[190:193], v[148:151], v[60:63]
	v_mfma_f32_16x16x32_bf16 v[28:31], v[208:211], v[148:151], v[28:31]
	v_mfma_f32_16x16x32_bf16 v[56:59], v[190:193], v[156:159], v[56:59]
	v_mfma_f32_16x16x32_bf16 v[24:27], v[208:211], v[156:159], v[24:27]
	v_mfma_f32_16x16x32_bf16 v[52:55], v[190:193], v[174:177], v[52:55]
	v_mfma_f32_16x16x32_bf16 v[20:23], v[208:211], v[174:177], v[20:23]
	v_mfma_f32_16x16x32_bf16 v[48:51], v[190:193], v[182:185], v[48:51]
	v_mfma_f32_16x16x32_bf16 v[16:19], v[208:211], v[182:185], v[16:19]
	s_barrier
	s_mov_b32 m0, s35
	v_lshl_add_u64 v[214:215], s[12:13], 0, v[164:165]
	ds_read_b128 v[144:147], v199 offset:16384
	ds_read_b128 v[148:151], v199 offset:17408
	ds_read_b128 v[152:155], v199 offset:18432
	ds_read_b128 v[156:159], v199 offset:19456
	ds_read_b128 v[160:163], v199 offset:20480
	ds_read_b128 v[174:177], v199 offset:21504
	ds_read_b128 v[178:181], v199 offset:22528
	ds_read_b128 v[182:185], v199 offset:23552
	global_load_lds_dwordx4 v[214:215], off
	v_lshl_add_u64 v[216:217], s[12:13], 0, v[166:167]
	s_mov_b32 m0, s44
	s_nop 0
	global_load_lds_dwordx4 v[216:217], off
	s_barrier
	s_waitcnt lgkmcnt(0)
	v_mfma_f32_16x16x32_bf16 v[108:111], v[128:131], v[144:147], v[108:111]
	v_mfma_f32_16x16x32_bf16 v[76:79], v[136:139], v[144:147], v[76:79]
	v_mfma_f32_16x16x32_bf16 v[104:107], v[128:131], v[152:155], v[104:107]
	v_mfma_f32_16x16x32_bf16 v[72:75], v[136:139], v[152:155], v[72:75]
	v_mfma_f32_16x16x32_bf16 v[100:103], v[128:131], v[160:163], v[100:103]
	v_mfma_f32_16x16x32_bf16 v[68:71], v[136:139], v[160:163], v[68:71]
	v_mfma_f32_16x16x32_bf16 v[96:99], v[128:131], v[178:181], v[96:99]
	v_mfma_f32_16x16x32_bf16 v[64:67], v[136:139], v[178:181], v[64:67]
	v_mfma_f32_16x16x32_bf16 v[108:111], v[132:135], v[148:151], v[108:111]
	v_mfma_f32_16x16x32_bf16 v[76:79], v[140:143], v[148:151], v[76:79]
	v_mfma_f32_16x16x32_bf16 v[104:107], v[132:135], v[156:159], v[104:107]
	v_mfma_f32_16x16x32_bf16 v[72:75], v[140:143], v[156:159], v[72:75]
	v_mfma_f32_16x16x32_bf16 v[100:103], v[132:135], v[174:177], v[100:103]
	v_mfma_f32_16x16x32_bf16 v[68:71], v[140:143], v[174:177], v[68:71]
	v_mfma_f32_16x16x32_bf16 v[96:99], v[132:135], v[182:185], v[96:99]
	v_mfma_f32_16x16x32_bf16 v[64:67], v[140:143], v[182:185], v[64:67]
	s_barrier
	s_add_u32 s6, s10, 0x100000
	s_addc_u32 s7, s11, 0
	s_mov_b32 m0, s60
	v_lshl_add_u64 v[128:129], s[6:7], 0, v[164:165]
	global_load_lds_dwordx4 v[128:129], off
	v_lshl_add_u64 v[128:129], s[6:7], 0, v[166:167]
	s_mov_b32 m0, s61
	s_nop 0
	global_load_lds_dwordx4 v[128:129], off
	s_waitcnt vmcnt(6)
	s_barrier
; #define WAIT_V(n) asm volatile("s_waitcnt vmcnt(" #n ")" ::: "memory")
; #define WAIT_L(n) asm volatile("s_waitcnt lgkmcnt(" #n ")" ::: "memory")
; #define BAR __builtin_amdgcn_s_barrier()
; #define SCHED __builtin_amdgcn_sched_barrier(0)
; template <class Get, class Epi>
; DI void gemm_stream(LAS unsigned char* lds, const int K, const int ld, Get get, Epi epi) {
;     ...
;             WAIT_V(6); BAR; MMA(1, 1, At, B1); BAR;
;             LDB(B0, 1, 0); SCHED; LDA(At, 1, 0); STAGE(SAo(0, 1), a2 + hstep);
;             WAIT_L(8); BAR; WAIT_L(0); MMA(0, 0, At, B0); BAR; SCHED;
;             LDB(B1, 1, 1); STAGE(SBo(1, 0), b3);
;             BAR; WAIT_L(0); MMA(0, 1, At, B1); BAR;
;             LDA(At, 1, 1); STAGE(SAo(1, 0), a3);
;             BAR; WAIT_L(0); MMA(1, 0, At, B0); BAR; SCHED;
	v_mfma_f32_16x16x32_bf16 v[44:47], v[186:189], v[144:147], v[44:47]
	v_mfma_f32_16x16x32_bf16 v[12:15], v[194:197], v[144:147], v[12:15]
	v_mfma_f32_16x16x32_bf16 v[40:43], v[186:189], v[152:155], v[40:43]
	v_mfma_f32_16x16x32_bf16 v[8:11], v[194:197], v[152:155], v[8:11]
	v_mfma_f32_16x16x32_bf16 v[36:39], v[186:189], v[160:163], v[36:39]
	v_mfma_f32_16x16x32_bf16 v[4:7], v[194:197], v[160:163], v[4:7]
	v_mfma_f32_16x16x32_bf16 v[32:35], v[186:189], v[178:181], v[32:35]
	v_mfma_f32_16x16x32_bf16 v[0:3], v[194:197], v[178:181], v[0:3]
	v_mfma_f32_16x16x32_bf16 v[44:47], v[190:193], v[148:151], v[44:47]
	v_mfma_f32_16x16x32_bf16 v[12:15], v[208:211], v[148:151], v[12:15]
	v_mfma_f32_16x16x32_bf16 v[40:43], v[190:193], v[156:159], v[40:43]
	v_mfma_f32_16x16x32_bf16 v[8:11], v[208:211], v[156:159], v[8:11]
	v_mfma_f32_16x16x32_bf16 v[36:39], v[190:193], v[174:177], v[36:39]
	v_mfma_f32_16x16x32_bf16 v[4:7], v[208:211], v[174:177], v[4:7]
	v_mfma_f32_16x16x32_bf16 v[32:35], v[190:193], v[182:185], v[32:35]
	v_mfma_f32_16x16x32_bf16 v[0:3], v[208:211], v[182:185], v[0:3]
	s_barrier
	ds_read_b128 v[128:131], v201
	ds_read_b128 v[132:135], v201 offset:1024
	ds_read_b128 v[136:139], v201 offset:2048
	ds_read_b128 v[140:143], v201 offset:3072
	s_add_u32 s6, s12, 0x100000
	s_addc_u32 s7, s13, 0
	s_mov_b32 m0, s45
	v_lshl_add_u64 v[186:187], s[6:7], 0, v[164:165]
	ds_read_b128 v[144:147], v199 offset:32768
	ds_read_b128 v[148:151], v199 offset:33792
	ds_read_b128 v[152:155], v199 offset:34816
	ds_read_b128 v[156:159], v199 offset:35840
	ds_read_b128 v[160:163], v199 offset:36864
	ds_read_b128 v[174:177], v199 offset:37888
	ds_read_b128 v[178:181], v199 offset:38912
	ds_read_b128 v[182:185], v199 offset:39936
	global_load_lds_dwordx4 v[186:187], off
	v_lshl_add_u64 v[186:187], s[6:7], 0, v[166:167]
	s_mov_b32 m0, s46
	s_nop 0
	global_load_lds_dwordx4 v[186:187], off
	s_waitcnt lgkmcnt(8)
	s_barrier
	s_waitcnt lgkmcnt(0)
	v_mfma_f32_16x16x32_bf16 v[124:127], v[128:131], v[144:147], v[124:127]
	v_mfma_f32_16x16x32_bf16 v[92:95], v[136:139], v[144:147], v[92:95]
	v_mfma_f32_16x16x32_bf16 v[120:123], v[128:131], v[152:155], v[120:123]
	v_mfma_f32_16x16x32_bf16 v[88:91], v[136:139], v[152:155], v[88:91]
	v_mfma_f32_16x16x32_bf16 v[116:119], v[128:131], v[160:163], v[116:119]
	v_mfma_f32_16x16x32_bf16 v[84:87], v[136:139], v[160:163], v[84:87]
	v_mfma_f32_16x16x32_bf16 v[112:115], v[128:131], v[178:181], v[112:115]
	v_mfma_f32_16x16x32_bf16 v[80:83], v[136:139], v[178:181], v[80:83]
	v_mfma_f32_16x16x32_bf16 v[124:127], v[132:135], v[148:151], v[124:127]
	v_mfma_f32_16x16x32_bf16 v[92:95], v[140:143], v[148:151], v[92:95]
	v_mfma_f32_16x16x32_bf16 v[120:123], v[132:135], v[156:159], v[120:123]
	v_mfma_f32_16x16x32_bf16 v[88:91], v[140:143], v[156:159], v[88:91]
	v_mfma_f32_16x16x32_bf16 v[116:119], v[132:135], v[174:177], v[116:119]
	v_mfma_f32_16x16x32_bf16 v[84:87], v[140:143], v[174:177], v[84:87]
	v_mfma_f32_16x16x32_bf16 v[112:115], v[132:135], v[182:185], v[112:115]
	v_mfma_f32_16x16x32_bf16 v[80:83], v[140:143], v[182:185], v[80:83]
	s_barrier
	s_mov_b32 m0, s64
	v_lshl_add_u64 v[204:205], v[204:205], 0, s[0:1]
	ds_read_b128 v[186:189], v202
	ds_read_b128 v[190:193], v202 offset:1024
	ds_read_b128 v[194:197], v202 offset:2048
	ds_read_b128 v[208:211], v202 offset:3072
	global_load_lds_dwordx4 v[204:205], off
	v_lshl_add_u64 v[204:205], v[212:213], 0, s[0:1]
	s_mov_b32 m0, s65
	s_nop 0
	global_load_lds_dwordx4 v[204:205], off
	s_barrier
	s_waitcnt lgkmcnt(0)
	v_mfma_f32_16x16x32_bf16 v[60:63], v[186:189], v[144:147], v[60:63]
	v_mfma_f32_16x16x32_bf16 v[28:31], v[194:197], v[144:147], v[28:31]
	v_mfma_f32_16x16x32_bf16 v[56:59], v[186:189], v[152:155], v[56:59]
	v_mfma_f32_16x16x32_bf16 v[24:27], v[194:197], v[152:155], v[24:27]
	v_mfma_f32_16x16x32_bf16 v[52:55], v[186:189], v[160:163], v[52:55]
	v_mfma_f32_16x16x32_bf16 v[20:23], v[194:197], v[160:163], v[20:23]
	v_mfma_f32_16x16x32_bf16 v[48:51], v[186:189], v[178:181], v[48:51]
	v_mfma_f32_16x16x32_bf16 v[16:19], v[194:197], v[178:181], v[16:19]
	v_mfma_f32_16x16x32_bf16 v[60:63], v[190:193], v[148:151], v[60:63]
	v_mfma_f32_16x16x32_bf16 v[28:31], v[208:211], v[148:151], v[28:31]
	v_mfma_f32_16x16x32_bf16 v[56:59], v[190:193], v[156:159], v[56:59]
	v_mfma_f32_16x16x32_bf16 v[24:27], v[208:211], v[156:159], v[24:27]
	v_mfma_f32_16x16x32_bf16 v[52:55], v[190:193], v[174:177], v[52:55]
	v_mfma_f32_16x16x32_bf16 v[20:23], v[208:211], v[174:177], v[20:23]
	v_mfma_f32_16x16x32_bf16 v[48:51], v[190:193], v[182:185], v[48:51]
	v_mfma_f32_16x16x32_bf16 v[16:19], v[208:211], v[182:185], v[16:19]
	s_barrier
	s_mov_b32 m0, s47
	v_lshl_add_u64 v[204:205], v[214:215], 0, s[0:1]
	ds_read_b128 v[144:147], v199 offset:49152
	ds_read_b128 v[148:151], v199 offset:50176
	ds_read_b128 v[152:155], v199 offset:51200
	ds_read_b128 v[156:159], v199 offset:52224
	ds_read_b128 v[160:163], v199 offset:53248
	ds_read_b128 v[174:177], v199 offset:54272
	ds_read_b128 v[178:181], v199 offset:55296
	ds_read_b128 v[182:185], v199 offset:56320
	global_load_lds_dwordx4 v[204:205], off
	v_lshl_add_u64 v[204:205], v[216:217], 0, s[0:1]
	s_mov_b32 m0, s48
	s_nop 0
	global_load_lds_dwordx4 v[204:205], off
	s_barrier
; #define WAIT_V(n) asm volatile("s_waitcnt vmcnt(" #n ")" ::: "memory")
; #define WAIT_L(n) asm volatile("s_waitcnt lgkmcnt(" #n ")" ::: "memory")
; #define BAR __builtin_amdgcn_s_barrier()
; #define SCHED __builtin_amdgcn_sched_barrier(0)
; template <class Get, class Epi>
; DI void gemm_stream(LAS unsigned char* lds, const int K, const int ld, Get get, Epi epi) {
;     ...
;             BAR; WAIT_L(0); MMA(1, 0, At, B0); BAR; SCHED;
;             STAGE(SBo(1, 1), b3 + hstep);
;             WAIT_V(6); BAR; MMA(1, 1, At, B1); BAR;
;         }
; DI void epi_resid(const Acc& acc, const P& p, int brow, int bcol, int layer, int gch, bool from_input) {
;     ...
; #pragma unroll
;     for (int bj = 0; bj < 2; ++bj)
; #pragma unroll
;         for (int n = 0; n < 2; ++n) {
;             const int c0 = bcol + bj * 128 + wc * 32 + n * 16 + fq * 4;
;             const f32x4 g = *(const f32x4*)(gate + c0);
;             f32x4 xv[2][4];
; #pragma unroll
;             for (int ai = 0; ai < 2; ++ai)
; #pragma unroll
;                 for (int m = 0; m < 4; ++m) {
;                     const int r = brow + ai * 128 + wr * 64 + m * 16 + fr;
;                     const float* sp = (from_input ? inrow(p, r) : xrow(p, r)) + c0;
;                     xv[ai][m] = *(const f32x4*)sp;
;                 }
;             __builtin_amdgcn_sched_barrier(0);
; #pragma unroll
;             for (int ai = 0; ai < 2; ++ai)
; #pragma unroll
;                 for (int m = 0; m < 4; ++m) {
;                     const int r = brow + ai * 128 + wr * 64 + m * 16 + fr;
;                     *(f32x4*)(xrow(p, r) + c0) = xv[ai][m] + g * acc[ai][bj][m][n];
;                 }
;             __builtin_amdgcn_sched_barrier(0);
;         }
	s_waitcnt lgkmcnt(0)
	v_mfma_f32_16x16x32_bf16 v[108:111], v[128:131], v[144:147], v[108:111]
	v_mfma_f32_16x16x32_bf16 v[76:79], v[136:139], v[144:147], v[76:79]
	v_mfma_f32_16x16x32_bf16 v[104:107], v[128:131], v[152:155], v[104:107]
	v_mfma_f32_16x16x32_bf16 v[72:75], v[136:139], v[152:155], v[72:75]
	v_mfma_f32_16x16x32_bf16 v[100:103], v[128:131], v[160:163], v[100:103]
	v_mfma_f32_16x16x32_bf16 v[68:71], v[136:139], v[160:163], v[68:71]
	v_mfma_f32_16x16x32_bf16 v[96:99], v[128:131], v[178:181], v[96:99]
	v_mfma_f32_16x16x32_bf16 v[64:67], v[136:139], v[178:181], v[64:67]
	v_mfma_f32_16x16x32_bf16 v[108:111], v[132:135], v[148:151], v[108:111]
	v_mfma_f32_16x16x32_bf16 v[76:79], v[140:143], v[148:151], v[76:79]
	v_mfma_f32_16x16x32_bf16 v[104:107], v[132:135], v[156:159], v[104:107]
	v_mfma_f32_16x16x32_bf16 v[72:75], v[140:143], v[156:159], v[72:75]
	v_mfma_f32_16x16x32_bf16 v[100:103], v[132:135], v[174:177], v[100:103]
	v_mfma_f32_16x16x32_bf16 v[68:71], v[140:143], v[174:177], v[68:71]
	v_mfma_f32_16x16x32_bf16 v[96:99], v[132:135], v[182:185], v[96:99]
	v_mfma_f32_16x16x32_bf16 v[64:67], v[140:143], v[182:185], v[64:67]
	s_barrier
	s_add_u32 s6, s10, 0x100080
	s_addc_u32 s7, s11, 0
	s_mov_b32 m0, s68
	v_lshl_add_u64 v[128:129], s[6:7], 0, v[164:165]
	global_load_lds_dwordx4 v[128:129], off
	v_lshl_add_u64 v[128:129], s[6:7], 0, v[166:167]
	s_mov_b32 m0, s69
	s_nop 0
	global_load_lds_dwordx4 v[128:129], off
	s_add_i32 s16, s16, 2
	s_add_u32 s14, s14, 0x100
	s_addc_u32 s15, s15, 0
	s_cmp_gt_u32 s16, 61
	s_mov_b64 s[6:7], s[8:9]
	s_waitcnt vmcnt(6)
	s_barrier
	v_mfma_f32_16x16x32_bf16 v[44:47], v[186:189], v[144:147], v[44:47]
	v_mfma_f32_16x16x32_bf16 v[12:15], v[194:197], v[144:147], v[12:15]
	v_mfma_f32_16x16x32_bf16 v[40:43], v[186:189], v[152:155], v[40:43]
	v_mfma_f32_16x16x32_bf16 v[8:11], v[194:197], v[152:155], v[8:11]
	v_mfma_f32_16x16x32_bf16 v[36:39], v[186:189], v[160:163], v[36:39]
	v_mfma_f32_16x16x32_bf16 v[4:7], v[194:197], v[160:163], v[4:7]
	v_mfma_f32_16x16x32_bf16 v[32:35], v[186:189], v[178:181], v[32:35]
	v_mfma_f32_16x16x32_bf16 v[0:3], v[194:197], v[178:181], v[0:3]
	v_mfma_f32_16x16x32_bf16 v[44:47], v[190:193], v[148:151], v[44:47]
	v_mfma_f32_16x16x32_bf16 v[12:15], v[208:211], v[148:151], v[12:15]
	v_mfma_f32_16x16x32_bf16 v[40:43], v[190:193], v[156:159], v[40:43]
	v_mfma_f32_16x16x32_bf16 v[8:11], v[208:211], v[156:159], v[8:11]
	v_mfma_f32_16x16x32_bf16 v[36:39], v[190:193], v[174:177], v[36:39]
	v_mfma_f32_16x16x32_bf16 v[4:7], v[208:211], v[174:177], v[4:7]
	v_mfma_f32_16x16x32_bf16 v[32:35], v[190:193], v[182:185], v[32:35]
	v_mfma_f32_16x16x32_bf16 v[0:3], v[208:211], v[182:185], v[0:3]
	s_barrier
	s_cbranch_scc0 .LBB0_2670
	s_lshl_b32 s12, s3, 21
	s_lshl_b32 s13, s2, 10
	s_lshr_b32 s16, s3, 4
	s_add_u32 s12, s12, s13
	s_mul_i32 s16, s16, 6
	s_add_i32 s16, s16, 32
	s_lshl_b32 s16, s16, 13
	s_add_u32 s16, s16, s13
	s_add_u32 s10, s26, s16
	s_addc_u32 s11, s27, 0
	s_add_u32 s6, s24, s12
	s_addc_u32 s7, s25, 0
	v_lshrrev_b32_e32 v224, 6, v206
	v_and_b32_e32 v225, 3, v224
	v_lshrrev_b32_e32 v224, 2, v224
	v_and_b32_e32 v205, 15, v206
	v_bfe_u32 v226, v206, 4, 2
	v_lshl_add_u32 v225, v225, 3, v226
	v_lshl_add_u32 v224, v224, 6, v205
	v_lshlrev_b32_e32 v205, 4, v225
	v_lshl_add_u32 v203, v224, 13, v205
	v_mov_b32_e32 v204, v203
	global_load_dwordx4 v[128:131], v205, s[10:11] offset:0
	global_load_dwordx4 v[132:135], v205, s[10:11] offset:64
	global_load_dwordx4 v[136:139], v205, s[10:11] offset:512
	global_load_dwordx4 v[140:143], v205, s[10:11] offset:576
	global_load_dwordx4 v[144:147], v203, s[6:7] offset:0
	global_load_dwordx4 v[148:151], v203, s[6:7] offset:64
	global_load_dwordx4 v[152:155], v203, s[6:7] offset:512
	global_load_dwordx4 v[156:159], v203, s[6:7] offset:576
	v_add_u32_e32 v203, 0x20000, v203
	global_load_dwordx4 v[160:163], v203, s[6:7] offset:0
	global_load_dwordx4 v[174:177], v203, s[6:7] offset:64
	global_load_dwordx4 v[178:181], v203, s[6:7] offset:512
	global_load_dwordx4 v[182:185], v203, s[6:7] offset:576
	v_add_u32_e32 v203, 0x20000, v203
	global_load_dwordx4 v[186:189], v203, s[6:7] offset:0
	global_load_dwordx4 v[190:193], v203, s[6:7] offset:64
	global_load_dwordx4 v[194:197], v203, s[6:7] offset:512
	global_load_dwordx4 v[208:211], v203, s[6:7] offset:576
	v_add_u32_e32 v203, 0x20000, v203
	global_load_dwordx4 v[212:215], v203, s[6:7] offset:0
	global_load_dwordx4 v[216:219], v203, s[6:7] offset:64
	global_load_dwordx4 v[220:223], v203, s[6:7] offset:512
	global_load_dwordx4 v[224:227], v203, s[6:7] offset:576
	v_add_u32_e32 v203, 0xa0000, v203
	s_waitcnt vmcnt(12)
	v_pk_fma_f32 v[124:125], v[124:125], v[128:129], v[144:145]
	v_pk_fma_f32 v[126:127], v[126:127], v[130:131], v[146:147]
	v_pk_fma_f32 v[92:93], v[92:93], v[132:133], v[148:149]
	v_pk_fma_f32 v[94:95], v[94:95], v[134:135], v[150:151]
	v_pk_fma_f32 v[60:61], v[60:61], v[136:137], v[152:153]
	v_pk_fma_f32 v[62:63], v[62:63], v[138:139], v[154:155]
	v_pk_fma_f32 v[28:29], v[28:29], v[140:141], v[156:157]
	v_pk_fma_f32 v[30:31], v[30:31], v[142:143], v[158:159]
	global_store_dwordx4 v204, v[124:127], s[6:7] offset:0
	global_store_dwordx4 v204, v[92:95], s[6:7] offset:64
	global_store_dwordx4 v204, v[60:63], s[6:7] offset:512
	global_store_dwordx4 v204, v[28:31], s[6:7] offset:576
	v_add_u32_e32 v204, 0x20000, v204
	global_load_dwordx4 v[144:147], v203, s[6:7] offset:0
	global_load_dwordx4 v[148:151], v203, s[6:7] offset:64
	global_load_dwordx4 v[152:155], v203, s[6:7] offset:512
	global_load_dwordx4 v[156:159], v203, s[6:7] offset:576
	v_add_u32_e32 v203, 0x20000, v203
	s_waitcnt vmcnt(16)
; #define EPI_DONE do { } while (0)
; DI void epi_resid(const Acc& acc, const P& p, int brow, int bcol, int layer, int gch, bool from_input) {
;     EPI_IDX
;     const float* gate = modv(p, layer, brow, gch);
; #pragma unroll
;     for (int bj = 0; bj < 2; ++bj)
; #pragma unroll
;         for (int n = 0; n < 2; ++n) {
;             const int c0 = bcol + bj * 128 + wc * 32 + n * 16 + fq * 4;
;             const f32x4 g = *(const f32x4*)(gate + c0);
;             f32x4 xv[2][4];
; #pragma unroll
;             for (int ai = 0; ai < 2; ++ai)
; #pragma unroll
;                 for (int m = 0; m < 4; ++m) {
;                     const int r = brow + ai * 128 + wr * 64 + m * 16 + fr;
;                     const float* sp = (from_input ? inrow(p, r) : xrow(p, r)) + c0;
;                     xv[ai][m] = *(const f32x4*)sp;
;                 }
;             __builtin_amdgcn_sched_barrier(0);
; #pragma unroll
;             for (int ai = 0; ai < 2; ++ai)
; #pragma unroll
;                 for (int m = 0; m < 4; ++m) {
;                     const int r = brow + ai * 128 + wr * 64 + m * 16 + fr;
;                     *(f32x4*)(xrow(p, r) + c0) = xv[ai][m] + g * acc[ai][bj][m][n];
;                 }
;             __builtin_amdgcn_sched_barrier(0);
;         }
;     EPI_DONE;
; }
	v_pk_fma_f32 v[120:121], v[120:121], v[128:129], v[160:161]
	v_pk_fma_f32 v[122:123], v[122:123], v[130:131], v[162:163]
	v_pk_fma_f32 v[88:89], v[88:89], v[132:133], v[174:175]
	v_pk_fma_f32 v[90:91], v[90:91], v[134:135], v[176:177]
	v_pk_fma_f32 v[56:57], v[56:57], v[136:137], v[178:179]
	v_pk_fma_f32 v[58:59], v[58:59], v[138:139], v[180:181]
	v_pk_fma_f32 v[24:25], v[24:25], v[140:141], v[182:183]
	v_pk_fma_f32 v[26:27], v[26:27], v[142:143], v[184:185]
	global_store_dwordx4 v204, v[120:123], s[6:7] offset:0
	global_store_dwordx4 v204, v[88:91], s[6:7] offset:64
	global_store_dwordx4 v204, v[56:59], s[6:7] offset:512
	global_store_dwordx4 v204, v[24:27], s[6:7] offset:576
	v_add_u32_e32 v204, 0x20000, v204
	global_load_dwordx4 v[160:163], v203, s[6:7] offset:0
	global_load_dwordx4 v[174:177], v203, s[6:7] offset:64
	global_load_dwordx4 v[178:181], v203, s[6:7] offset:512
	global_load_dwordx4 v[182:185], v203, s[6:7] offset:576
	v_add_u32_e32 v203, 0x20000, v203
	s_waitcnt vmcnt(20)
	v_pk_fma_f32 v[116:117], v[116:117], v[128:129], v[186:187]
	v_pk_fma_f32 v[118:119], v[118:119], v[130:131], v[188:189]
	v_pk_fma_f32 v[84:85], v[84:85], v[132:133], v[190:191]
	v_pk_fma_f32 v[86:87], v[86:87], v[134:135], v[192:193]
	v_pk_fma_f32 v[52:53], v[52:53], v[136:137], v[194:195]
	v_pk_fma_f32 v[54:55], v[54:55], v[138:139], v[196:197]
	v_pk_fma_f32 v[20:21], v[20:21], v[140:141], v[208:209]
	v_pk_fma_f32 v[22:23], v[22:23], v[142:143], v[210:211]
	global_store_dwordx4 v204, v[116:119], s[6:7] offset:0
	global_store_dwordx4 v204, v[84:87], s[6:7] offset:64
	global_store_dwordx4 v204, v[52:55], s[6:7] offset:512
	global_store_dwordx4 v204, v[20:23], s[6:7] offset:576
	v_add_u32_e32 v204, 0x20000, v204
	global_load_dwordx4 v[186:189], v203, s[6:7] offset:0
	global_load_dwordx4 v[190:193], v203, s[6:7] offset:64
	global_load_dwordx4 v[194:197], v203, s[6:7] offset:512
	global_load_dwordx4 v[208:211], v203, s[6:7] offset:576
	v_add_u32_e32 v203, 0x20000, v203
	s_waitcnt vmcnt(24)
	v_pk_fma_f32 v[112:113], v[112:113], v[128:129], v[212:213]
	v_pk_fma_f32 v[114:115], v[114:115], v[130:131], v[214:215]
	v_pk_fma_f32 v[80:81], v[80:81], v[132:133], v[216:217]
	v_pk_fma_f32 v[82:83], v[82:83], v[134:135], v[218:219]
	v_pk_fma_f32 v[48:49], v[48:49], v[136:137], v[220:221]
	v_pk_fma_f32 v[50:51], v[50:51], v[138:139], v[222:223]
	v_pk_fma_f32 v[16:17], v[16:17], v[140:141], v[224:225]
	v_pk_fma_f32 v[18:19], v[18:19], v[142:143], v[226:227]
	global_store_dwordx4 v204, v[112:115], s[6:7] offset:0
	global_store_dwordx4 v204, v[80:83], s[6:7] offset:64
	global_store_dwordx4 v204, v[48:51], s[6:7] offset:512
	global_store_dwordx4 v204, v[16:19], s[6:7] offset:576
	v_add_u32_e32 v204, 0xa0000, v204
	global_load_dwordx4 v[212:215], v203, s[6:7] offset:0
	global_load_dwordx4 v[216:219], v203, s[6:7] offset:64
	global_load_dwordx4 v[220:223], v203, s[6:7] offset:512
	global_load_dwordx4 v[224:227], v203, s[6:7] offset:576
	s_waitcnt vmcnt(24)
	v_pk_fma_f32 v[108:109], v[108:109], v[128:129], v[144:145]
	v_pk_fma_f32 v[110:111], v[110:111], v[130:131], v[146:147]
	v_pk_fma_f32 v[76:77], v[76:77], v[132:133], v[148:149]
	v_pk_fma_f32 v[78:79], v[78:79], v[134:135], v[150:151]
	v_pk_fma_f32 v[44:45], v[44:45], v[136:137], v[152:153]
	v_pk_fma_f32 v[46:47], v[46:47], v[138:139], v[154:155]
	v_pk_fma_f32 v[12:13], v[12:13], v[140:141], v[156:157]
	v_pk_fma_f32 v[14:15], v[14:15], v[142:143], v[158:159]
	global_store_dwordx4 v204, v[108:111], s[6:7] offset:0
	global_store_dwordx4 v204, v[76:79], s[6:7] offset:64
	global_store_dwordx4 v204, v[44:47], s[6:7] offset:512
	global_store_dwordx4 v204, v[12:15], s[6:7] offset:576
	v_add_u32_e32 v204, 0x20000, v204
	s_waitcnt vmcnt(20)
	v_pk_fma_f32 v[104:105], v[104:105], v[128:129], v[160:161]
	v_pk_fma_f32 v[106:107], v[106:107], v[130:131], v[162:163]
	v_pk_fma_f32 v[72:73], v[72:73], v[132:133], v[174:175]
	v_pk_fma_f32 v[74:75], v[74:75], v[134:135], v[176:177]
	v_pk_fma_f32 v[40:41], v[40:41], v[136:137], v[178:179]
	v_pk_fma_f32 v[42:43], v[42:43], v[138:139], v[180:181]
	v_pk_fma_f32 v[8:9], v[8:9], v[140:141], v[182:183]
	v_pk_fma_f32 v[10:11], v[10:11], v[142:143], v[184:185]
	global_store_dwordx4 v204, v[104:107], s[6:7] offset:0
	global_store_dwordx4 v204, v[72:75], s[6:7] offset:64
	global_store_dwordx4 v204, v[40:43], s[6:7] offset:512
	global_store_dwordx4 v204, v[8:11], s[6:7] offset:576
	v_add_u32_e32 v204, 0x20000, v204
	s_waitcnt vmcnt(16)
	v_pk_fma_f32 v[100:101], v[100:101], v[128:129], v[186:187]
	v_pk_fma_f32 v[102:103], v[102:103], v[130:131], v[188:189]
	v_pk_fma_f32 v[68:69], v[68:69], v[132:133], v[190:191]
	v_pk_fma_f32 v[70:71], v[70:71], v[134:135], v[192:193]
	v_pk_fma_f32 v[36:37], v[36:37], v[136:137], v[194:195]
	v_pk_fma_f32 v[38:39], v[38:39], v[138:139], v[196:197]
	v_pk_fma_f32 v[4:5], v[4:5], v[140:141], v[208:209]
	v_pk_fma_f32 v[6:7], v[6:7], v[142:143], v[210:211]
	global_store_dwordx4 v204, v[100:103], s[6:7] offset:0
	global_store_dwordx4 v204, v[68:71], s[6:7] offset:64
	global_store_dwordx4 v204, v[36:39], s[6:7] offset:512
	global_store_dwordx4 v204, v[4:7], s[6:7] offset:576
	v_add_u32_e32 v204, 0x20000, v204
	s_waitcnt vmcnt(12)
	v_pk_fma_f32 v[96:97], v[96:97], v[128:129], v[212:213]
	v_pk_fma_f32 v[98:99], v[98:99], v[130:131], v[214:215]
	v_pk_fma_f32 v[64:65], v[64:65], v[132:133], v[216:217]
	v_pk_fma_f32 v[66:67], v[66:67], v[134:135], v[218:219]
	v_pk_fma_f32 v[32:33], v[32:33], v[136:137], v[220:221]
	v_pk_fma_f32 v[34:35], v[34:35], v[138:139], v[222:223]
	v_pk_fma_f32 v[0:1], v[0:1], v[140:141], v[224:225]
	v_pk_fma_f32 v[2:3], v[2:3], v[142:143], v[226:227]
	global_store_dwordx4 v204, v[96:99], s[6:7] offset:0
	global_store_dwordx4 v204, v[64:67], s[6:7] offset:64
	global_store_dwordx4 v204, v[32:35], s[6:7] offset:512
	global_store_dwordx4 v204, v[0:3], s[6:7] offset:576
	s_branch .Lresid_latch_wout1

; #define WAIT_V(n) asm volatile("s_waitcnt vmcnt(" #n ")" ::: "memory")
; #define WAIT_L(n) asm volatile("s_waitcnt lgkmcnt(" #n ")" ::: "memory")
; #define BAR __builtin_amdgcn_s_barrier()
; #define SCHED __builtin_amdgcn_sched_barrier(0)
; template <class Get, class Epi>
; DI void gemm_stream(LAS unsigned char* lds, const int K, const int ld, Get get, Epi epi) {
;     ...
;             LDB(B0, 0, 0); SCHED; LDA(At, 0, 0); STAGE(SAo(1, 1), a1 + hstep);
;             WAIT_L(8); BAR; WAIT_L(0); MMA(0, 0, At, B0); BAR; SCHED;
;             LDB(B1, 0, 1); STAGE(SBo(0, 0), b2);
;             BAR; WAIT_L(0); MMA(0, 1, At, B1); BAR;
;             LDA(At, 0, 1); STAGE(SAo(0, 0), a2);
;             BAR; WAIT_L(0); MMA(1, 0, At, B0); BAR; SCHED;
;             STAGE(SBo(0, 1), b2 + hstep);
;             WAIT_V(6); BAR; MMA(1, 1, At, B1); BAR;
;             LDB(B0, 1, 0); SCHED; LDA(At, 1, 0); STAGE(SAo(0, 1), a2 + hstep);
;             WAIT_L(8); BAR; WAIT_L(0); MMA(0, 0, At, B0); BAR; SCHED;
.LBB0_3046:
	ds_read_b128 v[148:151], v142
	ds_read_b128 v[152:155], v142 offset:1024
	ds_read_b128 v[156:159], v142 offset:2048
	ds_read_b128 v[160:163], v142 offset:3072
	s_mov_b32 m0, s38
	v_lshl_add_u64 v[140:141], s[12:13], 0, v[134:135]
	ds_read_b128 v[164:167], v143
	ds_read_b128 v[168:171], v143 offset:1024
	ds_read_b128 v[172:175], v143 offset:2048
	ds_read_b128 v[176:179], v143 offset:3072
	ds_read_b128 v[180:183], v143 offset:4096
	ds_read_b128 v[184:187], v143 offset:5120
	ds_read_b128 v[188:191], v143 offset:6144
	ds_read_b128 v[192:195], v143 offset:7168
	global_load_lds_dwordx4 v[140:141], off
	v_lshl_add_u64 v[140:141], s[12:13], 0, v[136:137]
	s_mov_b32 m0, s39
	s_nop 0
	global_load_lds_dwordx4 v[140:141], off
	s_waitcnt lgkmcnt(8)
	s_barrier
	s_waitcnt lgkmcnt(0)
	v_mfma_f32_16x16x32_bf16 v[124:127], v[148:151], v[164:167], v[124:127]
	v_mfma_f32_16x16x32_bf16 v[116:119], v[156:159], v[164:167], v[116:119]
	v_mfma_f32_16x16x32_bf16 v[108:111], v[148:151], v[172:175], v[108:111]
	v_mfma_f32_16x16x32_bf16 v[100:103], v[156:159], v[172:175], v[100:103]
	v_mfma_f32_16x16x32_bf16 v[92:95], v[148:151], v[180:183], v[92:95]
	v_mfma_f32_16x16x32_bf16 v[84:87], v[156:159], v[180:183], v[84:87]
	v_mfma_f32_16x16x32_bf16 v[76:79], v[148:151], v[188:191], v[76:79]
	v_mfma_f32_16x16x32_bf16 v[68:71], v[156:159], v[188:191], v[68:71]
	v_mfma_f32_16x16x32_bf16 v[124:127], v[152:155], v[168:171], v[124:127]
	v_mfma_f32_16x16x32_bf16 v[116:119], v[160:163], v[168:171], v[116:119]
	v_mfma_f32_16x16x32_bf16 v[108:111], v[152:155], v[176:179], v[108:111]
	v_mfma_f32_16x16x32_bf16 v[100:103], v[160:163], v[176:179], v[100:103]
	v_mfma_f32_16x16x32_bf16 v[92:95], v[152:155], v[184:187], v[92:95]
	v_mfma_f32_16x16x32_bf16 v[84:87], v[160:163], v[184:187], v[84:87]
	v_mfma_f32_16x16x32_bf16 v[76:79], v[152:155], v[192:195], v[76:79]
	v_mfma_f32_16x16x32_bf16 v[68:71], v[160:163], v[192:195], v[68:71]
	s_barrier
	s_add_u32 s14, s12, 0xfff80080
	s_addc_u32 s15, s13, -1
	s_cmp_eq_u32 s56, 28
	s_cselect_b32 s17, s9, s15
	s_cselect_b32 s16, s8, s14
	s_cselect_b32 s15, s11, s55
	s_cselect_b32 s14, s10, s0
	s_mov_b32 m0, s40
	v_lshl_add_u64 v[140:141], s[14:15], 0, v[130:131]
	ds_read_b128 v[196:199], v144
	ds_read_b128 v[200:203], v144 offset:1024
	ds_read_b128 v[208:211], v144 offset:2048
	ds_read_b128 v[212:215], v144 offset:3072
	global_load_lds_dwordx4 v[140:141], off
	v_lshl_add_u64 v[204:205], s[14:15], 0, v[128:129]
	s_mov_b32 m0, s41
	s_nop 0
	global_load_lds_dwordx4 v[204:205], off
	s_barrier
	s_waitcnt lgkmcnt(0)
	v_mfma_f32_16x16x32_bf16 v[120:123], v[196:199], v[164:167], v[120:123]
	v_mfma_f32_16x16x32_bf16 v[112:115], v[208:211], v[164:167], v[112:115]
	v_mfma_f32_16x16x32_bf16 v[104:107], v[196:199], v[172:175], v[104:107]
	v_mfma_f32_16x16x32_bf16 v[96:99], v[208:211], v[172:175], v[96:99]
	v_mfma_f32_16x16x32_bf16 v[88:91], v[196:199], v[180:183], v[88:91]
	v_mfma_f32_16x16x32_bf16 v[80:83], v[208:211], v[180:183], v[80:83]
	v_mfma_f32_16x16x32_bf16 v[72:75], v[196:199], v[188:191], v[72:75]
	v_mfma_f32_16x16x32_bf16 v[64:67], v[208:211], v[188:191], v[64:67]
	v_mfma_f32_16x16x32_bf16 v[120:123], v[200:203], v[168:171], v[120:123]
	v_mfma_f32_16x16x32_bf16 v[112:115], v[212:215], v[168:171], v[112:115]
	v_mfma_f32_16x16x32_bf16 v[104:107], v[200:203], v[176:179], v[104:107]
	v_mfma_f32_16x16x32_bf16 v[96:99], v[212:215], v[176:179], v[96:99]
	v_mfma_f32_16x16x32_bf16 v[88:91], v[200:203], v[184:187], v[88:91]
	v_mfma_f32_16x16x32_bf16 v[80:83], v[212:215], v[184:187], v[80:83]
	v_mfma_f32_16x16x32_bf16 v[72:75], v[200:203], v[192:195], v[72:75]
	v_mfma_f32_16x16x32_bf16 v[64:67], v[212:215], v[192:195], v[64:67]
	s_barrier
	s_mov_b32 m0, s19
	v_lshl_add_u64 v[216:217], s[16:17], 0, v[130:131]
	ds_read_b128 v[164:167], v143 offset:16384
	ds_read_b128 v[168:171], v143 offset:17408
	ds_read_b128 v[172:175], v143 offset:18432
	ds_read_b128 v[176:179], v143 offset:19456
	ds_read_b128 v[180:183], v143 offset:20480
	ds_read_b128 v[184:187], v143 offset:21504
	ds_read_b128 v[188:191], v143 offset:22528
	ds_read_b128 v[192:195], v143 offset:23552
	global_load_lds_dwordx4 v[216:217], off
	v_lshl_add_u64 v[218:219], s[16:17], 0, v[128:129]
	s_mov_b32 m0, s20
	s_nop 0
	global_load_lds_dwordx4 v[218:219], off
	s_barrier
	s_waitcnt lgkmcnt(0)
	v_mfma_f32_16x16x32_bf16 v[60:63], v[148:151], v[164:167], v[60:63]
	v_mfma_f32_16x16x32_bf16 v[52:55], v[156:159], v[164:167], v[52:55]
	v_mfma_f32_16x16x32_bf16 v[44:47], v[148:151], v[172:175], v[44:47]
	v_mfma_f32_16x16x32_bf16 v[36:39], v[156:159], v[172:175], v[36:39]
	v_mfma_f32_16x16x32_bf16 v[28:31], v[148:151], v[180:183], v[28:31]
	v_mfma_f32_16x16x32_bf16 v[20:23], v[156:159], v[180:183], v[20:23]
	v_mfma_f32_16x16x32_bf16 v[12:15], v[148:151], v[188:191], v[12:15]
	v_mfma_f32_16x16x32_bf16 v[4:7], v[156:159], v[188:191], v[4:7]
	v_mfma_f32_16x16x32_bf16 v[60:63], v[152:155], v[168:171], v[60:63]
	v_mfma_f32_16x16x32_bf16 v[52:55], v[160:163], v[168:171], v[52:55]
	v_mfma_f32_16x16x32_bf16 v[44:47], v[152:155], v[176:179], v[44:47]
	v_mfma_f32_16x16x32_bf16 v[36:39], v[160:163], v[176:179], v[36:39]
	v_mfma_f32_16x16x32_bf16 v[28:31], v[152:155], v[184:187], v[28:31]
	v_mfma_f32_16x16x32_bf16 v[20:23], v[160:163], v[184:187], v[20:23]
	v_mfma_f32_16x16x32_bf16 v[12:15], v[152:155], v[192:195], v[12:15]
	v_mfma_f32_16x16x32_bf16 v[4:7], v[160:163], v[192:195], v[4:7]
	s_barrier
	s_add_u32 s58, s14, 0x80000
	s_addc_u32 s59, s15, 0
	s_mov_b32 m0, s42
	v_lshl_add_u64 v[148:149], s[58:59], 0, v[130:131]
	global_load_lds_dwordx4 v[148:149], off
	v_lshl_add_u64 v[148:149], s[58:59], 0, v[128:129]
	s_mov_b32 m0, s43
	s_nop 0
	global_load_lds_dwordx4 v[148:149], off
	s_waitcnt vmcnt(6)
	s_barrier
; #define WAIT_V(n) asm volatile("s_waitcnt vmcnt(" #n ")" ::: "memory")
; #define WAIT_L(n) asm volatile("s_waitcnt lgkmcnt(" #n ")" ::: "memory")
; #define BAR __builtin_amdgcn_s_barrier()
; #define SCHED __builtin_amdgcn_sched_barrier(0)
; template <class Get, class Epi>
; DI void gemm_stream(LAS unsigned char* lds, const int K, const int ld, Get get, Epi epi) {
;     ...
;             WAIT_V(6); BAR; MMA(1, 1, At, B1); BAR;
;             LDB(B0, 1, 0); SCHED; LDA(At, 1, 0); STAGE(SAo(0, 1), a2 + hstep);
;             WAIT_L(8); BAR; WAIT_L(0); MMA(0, 0, At, B0); BAR; SCHED;
;             LDB(B1, 1, 1); STAGE(SBo(1, 0), b3);
;             BAR; WAIT_L(0); MMA(0, 1, At, B1); BAR;
;             LDA(At, 1, 1); STAGE(SAo(1, 0), a3);
;             BAR; WAIT_L(0); MMA(1, 0, At, B0); BAR; SCHED;
;             STAGE(SBo(1, 1), b3 + hstep);
	v_mfma_f32_16x16x32_bf16 v[56:59], v[196:199], v[164:167], v[56:59]
	v_mfma_f32_16x16x32_bf16 v[48:51], v[208:211], v[164:167], v[48:51]
	v_mfma_f32_16x16x32_bf16 v[40:43], v[196:199], v[172:175], v[40:43]
	v_mfma_f32_16x16x32_bf16 v[32:35], v[208:211], v[172:175], v[32:35]
	v_mfma_f32_16x16x32_bf16 v[24:27], v[196:199], v[180:183], v[24:27]
	v_mfma_f32_16x16x32_bf16 v[16:19], v[208:211], v[180:183], v[16:19]
	v_mfma_f32_16x16x32_bf16 v[8:11], v[196:199], v[188:191], v[8:11]
	v_mfma_f32_16x16x32_bf16 v[0:3], v[208:211], v[188:191], v[0:3]
	v_mfma_f32_16x16x32_bf16 v[56:59], v[200:203], v[168:171], v[56:59]
	v_mfma_f32_16x16x32_bf16 v[48:51], v[212:215], v[168:171], v[48:51]
	v_mfma_f32_16x16x32_bf16 v[40:43], v[200:203], v[176:179], v[40:43]
	v_mfma_f32_16x16x32_bf16 v[32:35], v[212:215], v[176:179], v[32:35]
	v_mfma_f32_16x16x32_bf16 v[24:27], v[200:203], v[184:187], v[24:27]
	v_mfma_f32_16x16x32_bf16 v[16:19], v[212:215], v[184:187], v[16:19]
	v_mfma_f32_16x16x32_bf16 v[8:11], v[200:203], v[192:195], v[8:11]
	v_mfma_f32_16x16x32_bf16 v[0:3], v[212:215], v[192:195], v[0:3]
	s_barrier
	ds_read_b128 v[148:151], v145
	ds_read_b128 v[152:155], v145 offset:1024
	ds_read_b128 v[156:159], v145 offset:2048
	ds_read_b128 v[160:163], v145 offset:3072
	s_add_u32 s16, s16, 0x80000
	s_addc_u32 s17, s17, 0
	s_mov_b32 m0, s21
	v_lshl_add_u64 v[196:197], s[16:17], 0, v[130:131]
	ds_read_b128 v[164:167], v143 offset:32768
	ds_read_b128 v[168:171], v143 offset:33792
	ds_read_b128 v[172:175], v143 offset:34816
	ds_read_b128 v[176:179], v143 offset:35840
	ds_read_b128 v[180:183], v143 offset:36864
	ds_read_b128 v[184:187], v143 offset:37888
	ds_read_b128 v[188:191], v143 offset:38912
	ds_read_b128 v[192:195], v143 offset:39936
	global_load_lds_dwordx4 v[196:197], off
	v_lshl_add_u64 v[196:197], s[16:17], 0, v[128:129]
	s_mov_b32 m0, s28
	s_nop 0
	global_load_lds_dwordx4 v[196:197], off
	s_waitcnt lgkmcnt(8)
	s_barrier
	s_waitcnt lgkmcnt(0)
	v_mfma_f32_16x16x32_bf16 v[124:127], v[148:151], v[164:167], v[124:127]
	v_mfma_f32_16x16x32_bf16 v[116:119], v[156:159], v[164:167], v[116:119]
	v_mfma_f32_16x16x32_bf16 v[108:111], v[148:151], v[172:175], v[108:111]
	v_mfma_f32_16x16x32_bf16 v[100:103], v[156:159], v[172:175], v[100:103]
	v_mfma_f32_16x16x32_bf16 v[92:95], v[148:151], v[180:183], v[92:95]
	v_mfma_f32_16x16x32_bf16 v[84:87], v[156:159], v[180:183], v[84:87]
	v_mfma_f32_16x16x32_bf16 v[76:79], v[148:151], v[188:191], v[76:79]
	v_mfma_f32_16x16x32_bf16 v[68:71], v[156:159], v[188:191], v[68:71]
	v_mfma_f32_16x16x32_bf16 v[124:127], v[152:155], v[168:171], v[124:127]
	v_mfma_f32_16x16x32_bf16 v[116:119], v[160:163], v[168:171], v[116:119]
	v_mfma_f32_16x16x32_bf16 v[108:111], v[152:155], v[176:179], v[108:111]
	v_mfma_f32_16x16x32_bf16 v[100:103], v[160:163], v[176:179], v[100:103]
	v_mfma_f32_16x16x32_bf16 v[92:95], v[152:155], v[184:187], v[92:95]
	v_mfma_f32_16x16x32_bf16 v[84:87], v[160:163], v[184:187], v[84:87]
	v_mfma_f32_16x16x32_bf16 v[76:79], v[152:155], v[192:195], v[76:79]
	v_mfma_f32_16x16x32_bf16 v[68:71], v[160:163], v[192:195], v[68:71]
	s_barrier
	s_mov_b32 m0, s44
	v_lshl_add_u64 v[140:141], v[140:141], 0, s[6:7]
	ds_read_b128 v[196:199], v146
	ds_read_b128 v[200:203], v146 offset:1024
	ds_read_b128 v[208:211], v146 offset:2048
	ds_read_b128 v[212:215], v146 offset:3072
	global_load_lds_dwordx4 v[140:141], off
	v_lshl_add_u64 v[140:141], v[204:205], 0, s[6:7]
	s_mov_b32 m0, s45
	s_nop 0
	global_load_lds_dwordx4 v[140:141], off
	s_barrier
	s_waitcnt lgkmcnt(0)
	v_mfma_f32_16x16x32_bf16 v[120:123], v[196:199], v[164:167], v[120:123]
	v_mfma_f32_16x16x32_bf16 v[112:115], v[208:211], v[164:167], v[112:115]
	v_mfma_f32_16x16x32_bf16 v[104:107], v[196:199], v[172:175], v[104:107]
	v_mfma_f32_16x16x32_bf16 v[96:99], v[208:211], v[172:175], v[96:99]
	v_mfma_f32_16x16x32_bf16 v[88:91], v[196:199], v[180:183], v[88:91]
	v_mfma_f32_16x16x32_bf16 v[80:83], v[208:211], v[180:183], v[80:83]
	v_mfma_f32_16x16x32_bf16 v[72:75], v[196:199], v[188:191], v[72:75]
	v_mfma_f32_16x16x32_bf16 v[64:67], v[208:211], v[188:191], v[64:67]
	v_mfma_f32_16x16x32_bf16 v[120:123], v[200:203], v[168:171], v[120:123]
	v_mfma_f32_16x16x32_bf16 v[112:115], v[212:215], v[168:171], v[112:115]
	v_mfma_f32_16x16x32_bf16 v[104:107], v[200:203], v[176:179], v[104:107]
	v_mfma_f32_16x16x32_bf16 v[96:99], v[212:215], v[176:179], v[96:99]
	v_mfma_f32_16x16x32_bf16 v[88:91], v[200:203], v[184:187], v[88:91]
	v_mfma_f32_16x16x32_bf16 v[80:83], v[212:215], v[184:187], v[80:83]
	v_mfma_f32_16x16x32_bf16 v[72:75], v[200:203], v[192:195], v[72:75]
	v_mfma_f32_16x16x32_bf16 v[64:67], v[212:215], v[192:195], v[64:67]
	s_barrier
	s_mov_b32 m0, s29
	v_lshl_add_u64 v[140:141], v[216:217], 0, s[6:7]
	ds_read_b128 v[164:167], v143 offset:49152
	ds_read_b128 v[168:171], v143 offset:50176
	ds_read_b128 v[172:175], v143 offset:51200
	ds_read_b128 v[176:179], v143 offset:52224
	ds_read_b128 v[180:183], v143 offset:53248
	ds_read_b128 v[184:187], v143 offset:54272
	ds_read_b128 v[188:191], v143 offset:55296
	ds_read_b128 v[192:195], v143 offset:56320
	global_load_lds_dwordx4 v[140:141], off
	v_lshl_add_u64 v[140:141], v[218:219], 0, s[6:7]
	s_mov_b32 m0, s36
	s_nop 0
	global_load_lds_dwordx4 v[140:141], off
	s_barrier
; DI float silu_f(float g) { return g * __builtin_amdgcn_rcpf(1.f + __builtin_amdgcn_exp2f(-LOG2E * g)); }
; #define WAIT_V(n) asm volatile("s_waitcnt vmcnt(" #n ")" ::: "memory")
; #define WAIT_L(n) asm volatile("s_waitcnt lgkmcnt(" #n ")" ::: "memory")
; #define BAR __builtin_amdgcn_s_barrier()
; #define SCHED __builtin_amdgcn_sched_barrier(0)
; template <class Get, class Epi>
; DI void gemm_stream(LAS unsigned char* lds, const int K, const int ld, Get get, Epi epi) {
;     ...
;             BAR; WAIT_L(0); MMA(0, 1, At, B1); BAR;
;             LDA(At, 1, 1); STAGE(SAo(1, 0), a3);
;             BAR; WAIT_L(0); MMA(1, 0, At, B0); BAR; SCHED;
;             STAGE(SBo(1, 1), b3 + hstep);
;             WAIT_V(6); BAR; MMA(1, 1, At, B1); BAR;
;         }
; DI void epi_swiglu(const Acc& acc, int brow, int pn, bf16_t* hid) {
;     EPI_IDX
; #pragma unroll
;     for (int ai = 0; ai < 2; ++ai)
; #pragma unroll
;         for (int m = 0; m < 4; ++m) {
;             const int r = brow + ai * 128 + wr * 64 + m * 16 + fr;
;             bf16_t* rp = hid + (size_t)r * FF + pn * 128 + wc * 32 + fq * 4;
; #pragma unroll
;             for (int n = 0; n < 2; ++n) {
;                 const f32x4 g = acc[ai][0][m][n], u = acc[ai][1][m][n];
;                 float o[4];
; #pragma unroll
;                 for (int j = 0; j < 4; ++j) o[j] = silu_f(g[j]) * u[j];
;                 st4(rp + n * 16, o[0], o[1], o[2], o[3]);
;             }
;         }
	s_waitcnt lgkmcnt(0)
	v_mfma_f32_16x16x32_bf16 v[60:63], v[148:151], v[164:167], v[60:63]
	v_mfma_f32_16x16x32_bf16 v[52:55], v[156:159], v[164:167], v[52:55]
	v_mfma_f32_16x16x32_bf16 v[44:47], v[148:151], v[172:175], v[44:47]
	v_mfma_f32_16x16x32_bf16 v[36:39], v[156:159], v[172:175], v[36:39]
	v_mfma_f32_16x16x32_bf16 v[28:31], v[148:151], v[180:183], v[28:31]
	v_mfma_f32_16x16x32_bf16 v[20:23], v[156:159], v[180:183], v[20:23]
	v_mfma_f32_16x16x32_bf16 v[12:15], v[148:151], v[188:191], v[12:15]
	v_mfma_f32_16x16x32_bf16 v[4:7], v[156:159], v[188:191], v[4:7]
	v_mfma_f32_16x16x32_bf16 v[60:63], v[152:155], v[168:171], v[60:63]
	v_mfma_f32_16x16x32_bf16 v[52:55], v[160:163], v[168:171], v[52:55]
	v_mfma_f32_16x16x32_bf16 v[44:47], v[152:155], v[176:179], v[44:47]
	v_mfma_f32_16x16x32_bf16 v[36:39], v[160:163], v[176:179], v[36:39]
	v_mfma_f32_16x16x32_bf16 v[28:31], v[152:155], v[184:187], v[28:31]
	v_mfma_f32_16x16x32_bf16 v[20:23], v[160:163], v[184:187], v[20:23]
	v_mfma_f32_16x16x32_bf16 v[12:15], v[152:155], v[192:195], v[12:15]
	v_mfma_f32_16x16x32_bf16 v[4:7], v[160:163], v[192:195], v[4:7]
	s_barrier
	s_add_u32 s14, s14, 0x80080
	s_addc_u32 s15, s15, 0
	s_mov_b32 m0, s46
	v_lshl_add_u64 v[140:141], s[14:15], 0, v[130:131]
	global_load_lds_dwordx4 v[140:141], off
	v_lshl_add_u64 v[140:141], s[14:15], 0, v[128:129]
	s_mov_b32 m0, s47
	s_nop 0
	global_load_lds_dwordx4 v[140:141], off
	s_add_i32 s56, s56, 2
	s_add_u32 s12, s12, 0x100
	s_addc_u32 s13, s13, 0
	s_add_u32 s0, s0, 0x100
	s_addc_u32 s55, s55, 0
	s_cmp_gt_u32 s56, 29
	s_waitcnt vmcnt(6)
	s_barrier
	v_mfma_f32_16x16x32_bf16 v[56:59], v[196:199], v[164:167], v[56:59]
	v_mfma_f32_16x16x32_bf16 v[48:51], v[208:211], v[164:167], v[48:51]
	v_mfma_f32_16x16x32_bf16 v[40:43], v[196:199], v[172:175], v[40:43]
	v_mfma_f32_16x16x32_bf16 v[32:35], v[208:211], v[172:175], v[32:35]
	v_mfma_f32_16x16x32_bf16 v[24:27], v[196:199], v[180:183], v[24:27]
	v_mfma_f32_16x16x32_bf16 v[16:19], v[208:211], v[180:183], v[16:19]
	v_mfma_f32_16x16x32_bf16 v[8:11], v[196:199], v[188:191], v[8:11]
	v_mfma_f32_16x16x32_bf16 v[0:3], v[208:211], v[188:191], v[0:3]
	v_mfma_f32_16x16x32_bf16 v[56:59], v[200:203], v[168:171], v[56:59]
	v_mfma_f32_16x16x32_bf16 v[48:51], v[212:215], v[168:171], v[48:51]
	v_mfma_f32_16x16x32_bf16 v[40:43], v[200:203], v[176:179], v[40:43]
	v_mfma_f32_16x16x32_bf16 v[32:35], v[212:215], v[176:179], v[32:35]
	v_mfma_f32_16x16x32_bf16 v[24:27], v[200:203], v[184:187], v[24:27]
	v_mfma_f32_16x16x32_bf16 v[16:19], v[212:215], v[184:187], v[16:19]
	v_mfma_f32_16x16x32_bf16 v[8:11], v[200:203], v[192:195], v[8:11]
	v_mfma_f32_16x16x32_bf16 v[0:3], v[212:215], v[192:195], v[0:3]
	s_barrier
	s_cbranch_scc0 .LBB0_3046
	s_lshr_b32 s0, s53, 4
	s_lshl_b32 s12, s53, 8
	s_mulk_i32 s0, 0x1100
	s_and_b32 s12, s12, 0xf00
	s_add_i32 s0, s0, s12
	s_lshl_b32 s12, s54, 7
	s_ashr_i32 s13, s12, 31
	s_addk_i32 s0, 0x100
	v_mov_b32_e32 v132, v206
	s_lshl_b64 s[12:13], s[12:13], 1
	s_add_u32 s12, s23, s12
	v_ashrrev_i32_e32 v140, 2, v132
	v_and_b32_e32 v140, 0xffffffc0, v140
	v_and_or_b32 v141, v132, 15, s0
	s_addc_u32 s13, s35, s13
	v_lshrrev_b32_e32 v148, 1, v132
	v_and_b32_e32 v132, 0xc0, v132
	v_add_u32_e32 v147, v141, v140
	v_lshl_add_u64 v[140:141], s[12:13], 0, v[132:133]
	v_and_b32_e32 v132, 24, v148
	v_mul_f32_e32 v148, 0xbfb8aa3b, v124
	v_exp_f32_e32 v148, v148
	v_mul_f32_e32 v149, 0xbfb8aa3b, v125
	v_exp_f32_e32 v149, v149
	v_lshl_add_u64 v[140:141], v[140:141], 0, v[132:133]
	v_add_f32_e32 v132, 1.0, v148
	v_rcp_f32_e32 v148, v132
	v_add_f32_e32 v132, 1.0, v149
	v_mul_f32_e32 v149, 0xbfb8aa3b, v126
	v_exp_f32_e32 v150, v149
	v_mul_f32_e32 v149, 0xbfb8aa3b, v127
	v_exp_f32_e32 v151, v149
	v_rcp_f32_e32 v149, v132
	v_add_f32_e32 v132, 1.0, v150
	v_rcp_f32_e32 v150, v132
	v_add_f32_e32 v132, 1.0, v151
	v_rcp_f32_e32 v151, v132
	v_pk_mul_f32 v[124:125], v[124:125], v[148:149]
	v_mad_i64_i32 v[152:153], s[12:13], v147, s37, v[140:141]
	v_pk_mul_f32 v[120:121], v[124:125], v[120:121]
	v_pk_mul_f32 v[124:125], v[126:127], v[150:151]
	v_cvt_pk_bf16_f32 v120, v120, v121
	v_mul_f32_e32 v121, 0xbfb8aa3b, v116
	v_pk_mul_f32 v[122:123], v[124:125], v[122:123]
	v_exp_f32_e32 v124, v121
	v_mul_f32_e32 v121, 0xbfb8aa3b, v117
	v_exp_f32_e32 v125, v121
	v_cvt_pk_bf16_f32 v121, v122, v123
	v_add_f32_e32 v122, 1.0, v124
	v_mul_f32_e32 v124, 0xbfb8aa3b, v118
	v_add_f32_e32 v123, 1.0, v125
	v_mul_f32_e32 v125, 0xbfb8aa3b, v119
	v_exp_f32_e32 v124, v124
	v_exp_f32_e32 v125, v125
	v_rcp_f32_e32 v122, v122
	v_rcp_f32_e32 v123, v123
	v_add_f32_e32 v124, 1.0, v124
	v_add_f32_e32 v125, 1.0, v125
	v_rcp_f32_e32 v124, v124
	v_rcp_f32_e32 v125, v125
	v_pk_mul_f32 v[116:117], v[116:117], v[122:123]
	s_and_b64 vcc, exec, s[4:5]
	v_pk_mul_f32 v[112:113], v[116:117], v[112:113]
	v_pk_mul_f32 v[116:117], v[118:119], v[124:125]
	v_cvt_pk_bf16_f32 v112, v112, v113
	v_pk_mul_f32 v[114:115], v[116:117], v[114:115]
	v_or_b32_e32 v116, 16, v147
	v_cvt_pk_bf16_f32 v113, v114, v115
	global_store_dwordx2 v[152:153], v[112:113], off offset:32
	v_mul_f32_e32 v112, 0xbfb8aa3b, v108
	v_mul_f32_e32 v113, 0xbfb8aa3b, v109
	v_exp_f32_e32 v112, v112
	v_exp_f32_e32 v113, v113
	v_mul_f32_e32 v114, 0xbfb8aa3b, v110
	v_mul_f32_e32 v115, 0xbfb8aa3b, v111
	v_exp_f32_e32 v114, v114
	v_exp_f32_e32 v115, v115
	v_add_f32_e32 v112, 1.0, v112
	v_add_f32_e32 v113, 1.0, v113
	v_rcp_f32_e32 v112, v112
	v_rcp_f32_e32 v113, v113
	v_add_f32_e32 v114, 1.0, v114
	v_add_f32_e32 v115, 1.0, v115
	v_rcp_f32_e32 v114, v114
	v_rcp_f32_e32 v115, v115
	v_pk_mul_f32 v[108:109], v[108:109], v[112:113]
	v_mad_i64_i32 v[116:117], s[12:13], v116, s37, v[140:141]
; DI float silu_f(float g) { return g * __builtin_amdgcn_rcpf(1.f + __builtin_amdgcn_exp2f(-LOG2E * g)); }
; DI void epi_swiglu(const Acc& acc, int brow, int pn, bf16_t* hid) {
;     EPI_IDX
; #pragma unroll
;     for (int ai = 0; ai < 2; ++ai)
; #pragma unroll
;         for (int m = 0; m < 4; ++m) {
;             const int r = brow + ai * 128 + wr * 64 + m * 16 + fr;
;             bf16_t* rp = hid + (size_t)r * FF + pn * 128 + wc * 32 + fq * 4;
; #pragma unroll
;             for (int n = 0; n < 2; ++n) {
;                 const f32x4 g = acc[ai][0][m][n], u = acc[ai][1][m][n];
;                 float o[4];
; #pragma unroll
;                 for (int j = 0; j < 4; ++j) o[j] = silu_f(g[j]) * u[j];
;                 st4(rp + n * 16, o[0], o[1], o[2], o[3]);
;             }
;         }
	v_pk_mul_f32 v[104:105], v[108:109], v[104:105]
	v_pk_mul_f32 v[108:109], v[110:111], v[114:115]
	v_cvt_pk_bf16_f32 v104, v104, v105
	v_mul_f32_e32 v105, 0xbfb8aa3b, v100
	v_pk_mul_f32 v[106:107], v[108:109], v[106:107]
	v_exp_f32_e32 v108, v105
	v_mul_f32_e32 v105, 0xbfb8aa3b, v101
	v_exp_f32_e32 v109, v105
	v_cvt_pk_bf16_f32 v105, v106, v107
	v_add_f32_e32 v106, 1.0, v108
	v_mul_f32_e32 v108, 0xbfb8aa3b, v102
	v_add_f32_e32 v107, 1.0, v109
	v_mul_f32_e32 v109, 0xbfb8aa3b, v103
	v_exp_f32_e32 v108, v108
	v_exp_f32_e32 v109, v109
	v_rcp_f32_e32 v106, v106
	v_rcp_f32_e32 v107, v107
	v_add_f32_e32 v108, 1.0, v108
	v_add_f32_e32 v109, 1.0, v109
	v_rcp_f32_e32 v108, v108
	v_rcp_f32_e32 v109, v109
	v_pk_mul_f32 v[100:101], v[100:101], v[106:107]
	s_mov_b32 s54, s49
	v_pk_mul_f32 v[96:97], v[100:101], v[96:97]
	v_pk_mul_f32 v[100:101], v[102:103], v[108:109]
	v_cvt_pk_bf16_f32 v96, v96, v97
	v_pk_mul_f32 v[98:99], v[100:101], v[98:99]
	v_or_b32_e32 v100, 32, v147
	v_cvt_pk_bf16_f32 v97, v98, v99
	global_store_dwordx2 v[116:117], v[96:97], off offset:32
	v_mul_f32_e32 v96, 0xbfb8aa3b, v92
	v_mul_f32_e32 v97, 0xbfb8aa3b, v93
	v_exp_f32_e32 v96, v96
	v_exp_f32_e32 v97, v97
	v_mul_f32_e32 v98, 0xbfb8aa3b, v94
	v_mul_f32_e32 v99, 0xbfb8aa3b, v95
	v_exp_f32_e32 v98, v98
	v_exp_f32_e32 v99, v99
	v_add_f32_e32 v96, 1.0, v96
	v_add_f32_e32 v97, 1.0, v97
	v_rcp_f32_e32 v96, v96
	v_rcp_f32_e32 v97, v97
	v_add_f32_e32 v98, 1.0, v98
	v_add_f32_e32 v99, 1.0, v99
	v_rcp_f32_e32 v98, v98
	v_rcp_f32_e32 v99, v99
	v_pk_mul_f32 v[92:93], v[92:93], v[96:97]
	v_mad_i64_i32 v[100:101], s[12:13], v100, s37, v[140:141]
	v_pk_mul_f32 v[88:89], v[92:93], v[88:89]
	v_pk_mul_f32 v[92:93], v[94:95], v[98:99]
	v_cvt_pk_bf16_f32 v88, v88, v89
	v_mul_f32_e32 v89, 0xbfb8aa3b, v84
	v_pk_mul_f32 v[90:91], v[92:93], v[90:91]
	v_exp_f32_e32 v92, v89
	v_mul_f32_e32 v89, 0xbfb8aa3b, v85
	v_exp_f32_e32 v93, v89
	v_cvt_pk_bf16_f32 v89, v90, v91
	v_add_f32_e32 v90, 1.0, v92
	v_mul_f32_e32 v92, 0xbfb8aa3b, v86
	v_add_f32_e32 v91, 1.0, v93
	v_mul_f32_e32 v93, 0xbfb8aa3b, v87
	v_exp_f32_e32 v92, v92
	v_exp_f32_e32 v93, v93
	v_rcp_f32_e32 v90, v90
	v_rcp_f32_e32 v91, v91
	v_add_f32_e32 v92, 1.0, v92
	v_add_f32_e32 v93, 1.0, v93
	v_rcp_f32_e32 v92, v92
	v_rcp_f32_e32 v93, v93
	v_pk_mul_f32 v[84:85], v[84:85], v[90:91]
	s_mov_b32 s53, s52
	v_pk_mul_f32 v[80:81], v[84:85], v[80:81]
	v_pk_mul_f32 v[84:85], v[86:87], v[92:93]
	v_cvt_pk_bf16_f32 v80, v80, v81
	v_pk_mul_f32 v[82:83], v[84:85], v[82:83]
	v_or_b32_e32 v84, 48, v147
	v_cvt_pk_bf16_f32 v81, v82, v83
	global_store_dwordx2 v[100:101], v[80:81], off offset:32
	v_mul_f32_e32 v80, 0xbfb8aa3b, v76
	v_mul_f32_e32 v81, 0xbfb8aa3b, v77
	v_exp_f32_e32 v80, v80
	v_exp_f32_e32 v81, v81
	v_mul_f32_e32 v82, 0xbfb8aa3b, v78
	v_mul_f32_e32 v83, 0xbfb8aa3b, v79
	v_exp_f32_e32 v82, v82
	v_exp_f32_e32 v83, v83
	v_add_f32_e32 v80, 1.0, v80
	v_add_f32_e32 v81, 1.0, v81
	v_rcp_f32_e32 v80, v80
	v_rcp_f32_e32 v81, v81
	v_add_f32_e32 v82, 1.0, v82
	v_add_f32_e32 v83, 1.0, v83
	v_rcp_f32_e32 v82, v82
	v_rcp_f32_e32 v83, v83
	v_pk_mul_f32 v[76:77], v[76:77], v[80:81]
	v_mad_i64_i32 v[84:85], s[12:13], v84, s37, v[140:141]
	v_pk_mul_f32 v[72:73], v[76:77], v[72:73]
	v_pk_mul_f32 v[76:77], v[78:79], v[82:83]
	v_cvt_pk_bf16_f32 v72, v72, v73
	v_mul_f32_e32 v73, 0xbfb8aa3b, v68
	v_pk_mul_f32 v[74:75], v[76:77], v[74:75]
	v_exp_f32_e32 v76, v73
	v_mul_f32_e32 v73, 0xbfb8aa3b, v69
	v_exp_f32_e32 v77, v73
	v_cvt_pk_bf16_f32 v73, v74, v75
	v_add_f32_e32 v74, 1.0, v76
	v_mul_f32_e32 v76, 0xbfb8aa3b, v70
	v_add_f32_e32 v75, 1.0, v77
	v_mul_f32_e32 v77, 0xbfb8aa3b, v71
	v_exp_f32_e32 v76, v76
	v_exp_f32_e32 v77, v77
	v_rcp_f32_e32 v74, v74
	v_rcp_f32_e32 v75, v75
	v_add_f32_e32 v76, 1.0, v76
	v_add_f32_e32 v77, 1.0, v77
	v_rcp_f32_e32 v76, v76
	v_rcp_f32_e32 v77, v77
	v_pk_mul_f32 v[68:69], v[68:69], v[74:75]
	s_mov_b64 s[14:15], s[10:11]
	v_pk_mul_f32 v[64:65], v[68:69], v[64:65]
	v_pk_mul_f32 v[68:69], v[70:71], v[76:77]
	v_cvt_pk_bf16_f32 v64, v64, v65
	v_pk_mul_f32 v[66:67], v[68:69], v[66:67]
	v_add_u32_e32 v68, 0x80, v147
	v_cvt_pk_bf16_f32 v65, v66, v67
	global_store_dwordx2 v[84:85], v[64:65], off offset:32
	v_mul_f32_e32 v64, 0xbfb8aa3b, v60
	v_mul_f32_e32 v65, 0xbfb8aa3b, v61
	v_exp_f32_e32 v64, v64
	v_exp_f32_e32 v65, v65
	v_mul_f32_e32 v66, 0xbfb8aa3b, v62
	v_mul_f32_e32 v67, 0xbfb8aa3b, v63
	v_exp_f32_e32 v66, v66
	v_exp_f32_e32 v67, v67
	v_add_f32_e32 v64, 1.0, v64
	v_add_f32_e32 v65, 1.0, v65
	v_rcp_f32_e32 v64, v64
	v_rcp_f32_e32 v65, v65
	v_add_f32_e32 v66, 1.0, v66
	v_add_f32_e32 v67, 1.0, v67
	v_rcp_f32_e32 v66, v66
	v_rcp_f32_e32 v67, v67
	v_pk_mul_f32 v[60:61], v[60:61], v[64:65]
	v_mad_i64_i32 v[68:69], s[12:13], v68, s37, v[140:141]
	v_pk_mul_f32 v[56:57], v[60:61], v[56:57]
	v_pk_mul_f32 v[60:61], v[62:63], v[66:67]
	v_cvt_pk_bf16_f32 v56, v56, v57
	v_mul_f32_e32 v57, 0xbfb8aa3b, v52
	v_pk_mul_f32 v[58:59], v[60:61], v[58:59]
	v_exp_f32_e32 v60, v57
	v_mul_f32_e32 v57, 0xbfb8aa3b, v53
	v_exp_f32_e32 v61, v57
	v_cvt_pk_bf16_f32 v57, v58, v59
	v_add_f32_e32 v58, 1.0, v60
	v_mul_f32_e32 v60, 0xbfb8aa3b, v54
	v_add_f32_e32 v59, 1.0, v61
	v_mul_f32_e32 v61, 0xbfb8aa3b, v55
	v_exp_f32_e32 v60, v60
	v_exp_f32_e32 v61, v61
	v_rcp_f32_e32 v58, v58
	v_rcp_f32_e32 v59, v59
	v_add_f32_e32 v60, 1.0, v60
	v_add_f32_e32 v61, 1.0, v61
	v_rcp_f32_e32 v60, v60
; DI float silu_f(float g) { return g * __builtin_amdgcn_rcpf(1.f + __builtin_amdgcn_exp2f(-LOG2E * g)); }
; #define WAIT_V(n) asm volatile("s_waitcnt vmcnt(" #n ")" ::: "memory")
; #define BAR __builtin_amdgcn_s_barrier()
; template <class Get, class Epi>
; DI void gemm_stream(LAS unsigned char* lds, const int K, const int ld, Get get, Epi epi) {
;     ...
;         epi(acc, cur);
;         if (!has_next) break;
;         ZERO_ACC;
;         cur = nxt; cA = nA; cB = nB; ++ui;
;     }
;     WAIT_V(0);
;     if (wr == 0) BAR;
; DI void epi_swiglu(const Acc& acc, int brow, int pn, bf16_t* hid) {
;     EPI_IDX
; #pragma unroll
;     for (int ai = 0; ai < 2; ++ai)
; #pragma unroll
;         for (int m = 0; m < 4; ++m) {
;             const int r = brow + ai * 128 + wr * 64 + m * 16 + fr;
;             bf16_t* rp = hid + (size_t)r * FF + pn * 128 + wc * 32 + fq * 4;
; #pragma unroll
;             for (int n = 0; n < 2; ++n) {
;                 const f32x4 g = acc[ai][0][m][n], u = acc[ai][1][m][n];
;                 float o[4];
; #pragma unroll
;                 for (int j = 0; j < 4; ++j) o[j] = silu_f(g[j]) * u[j];
;                 st4(rp + n * 16, o[0], o[1], o[2], o[3]);
;             }
;         }
	v_rcp_f32_e32 v61, v61
	v_pk_mul_f32 v[52:53], v[52:53], v[58:59]
	global_store_dwordx2 v[152:153], v[120:121], off
	v_pk_mul_f32 v[48:49], v[52:53], v[48:49]
	v_pk_mul_f32 v[52:53], v[54:55], v[60:61]
	v_cvt_pk_bf16_f32 v48, v48, v49
	v_pk_mul_f32 v[50:51], v[52:53], v[50:51]
	v_add_u32_e32 v52, 0x90, v147
	v_cvt_pk_bf16_f32 v49, v50, v51
	global_store_dwordx2 v[68:69], v[48:49], off offset:32
	v_mul_f32_e32 v48, 0xbfb8aa3b, v44
	v_mul_f32_e32 v49, 0xbfb8aa3b, v45
	v_exp_f32_e32 v48, v48
	v_exp_f32_e32 v49, v49
	v_mul_f32_e32 v50, 0xbfb8aa3b, v46
	v_mul_f32_e32 v51, 0xbfb8aa3b, v47
	v_exp_f32_e32 v50, v50
	v_exp_f32_e32 v51, v51
	v_add_f32_e32 v48, 1.0, v48
	v_add_f32_e32 v49, 1.0, v49
	v_rcp_f32_e32 v48, v48
	v_rcp_f32_e32 v49, v49
	v_add_f32_e32 v50, 1.0, v50
	v_add_f32_e32 v51, 1.0, v51
	v_rcp_f32_e32 v50, v50
	v_rcp_f32_e32 v51, v51
	v_pk_mul_f32 v[44:45], v[44:45], v[48:49]
	v_mad_i64_i32 v[52:53], s[12:13], v52, s37, v[140:141]
	v_pk_mul_f32 v[40:41], v[44:45], v[40:41]
	v_pk_mul_f32 v[44:45], v[46:47], v[50:51]
	v_cvt_pk_bf16_f32 v40, v40, v41
	v_mul_f32_e32 v41, 0xbfb8aa3b, v36
	v_pk_mul_f32 v[42:43], v[44:45], v[42:43]
	v_exp_f32_e32 v44, v41
	v_mul_f32_e32 v41, 0xbfb8aa3b, v37
	v_exp_f32_e32 v45, v41
	v_cvt_pk_bf16_f32 v41, v42, v43
	v_add_f32_e32 v42, 1.0, v44
	v_mul_f32_e32 v44, 0xbfb8aa3b, v38
	v_add_f32_e32 v43, 1.0, v45
	v_mul_f32_e32 v45, 0xbfb8aa3b, v39
	v_exp_f32_e32 v44, v44
	v_exp_f32_e32 v45, v45
	v_rcp_f32_e32 v42, v42
	v_rcp_f32_e32 v43, v43
	v_add_f32_e32 v44, 1.0, v44
	v_add_f32_e32 v45, 1.0, v45
	v_rcp_f32_e32 v44, v44
	v_rcp_f32_e32 v45, v45
	v_pk_mul_f32 v[36:37], v[36:37], v[42:43]
	global_store_dwordx2 v[116:117], v[104:105], off
	v_pk_mul_f32 v[32:33], v[36:37], v[32:33]
	v_pk_mul_f32 v[36:37], v[38:39], v[44:45]
	v_cvt_pk_bf16_f32 v32, v32, v33
	v_pk_mul_f32 v[34:35], v[36:37], v[34:35]
	v_add_u32_e32 v36, 0xa0, v147
	v_cvt_pk_bf16_f32 v33, v34, v35
	global_store_dwordx2 v[52:53], v[32:33], off offset:32
	v_mul_f32_e32 v32, 0xbfb8aa3b, v28
	v_mul_f32_e32 v33, 0xbfb8aa3b, v29
	v_exp_f32_e32 v32, v32
	v_exp_f32_e32 v33, v33
	v_mul_f32_e32 v34, 0xbfb8aa3b, v30
	v_mul_f32_e32 v35, 0xbfb8aa3b, v31
	v_exp_f32_e32 v34, v34
	v_exp_f32_e32 v35, v35
	v_add_f32_e32 v32, 1.0, v32
	v_add_f32_e32 v33, 1.0, v33
	v_rcp_f32_e32 v32, v32
	v_rcp_f32_e32 v33, v33
	v_add_f32_e32 v34, 1.0, v34
	v_add_f32_e32 v35, 1.0, v35
	v_rcp_f32_e32 v34, v34
	v_rcp_f32_e32 v35, v35
	v_pk_mul_f32 v[28:29], v[28:29], v[32:33]
	v_mad_i64_i32 v[36:37], s[12:13], v36, s37, v[140:141]
	v_pk_mul_f32 v[24:25], v[28:29], v[24:25]
	v_pk_mul_f32 v[28:29], v[30:31], v[34:35]
	v_cvt_pk_bf16_f32 v24, v24, v25
	v_mul_f32_e32 v25, 0xbfb8aa3b, v20
	v_pk_mul_f32 v[26:27], v[28:29], v[26:27]
	v_exp_f32_e32 v28, v25
	v_mul_f32_e32 v25, 0xbfb8aa3b, v21
	v_exp_f32_e32 v29, v25
	v_cvt_pk_bf16_f32 v25, v26, v27
	v_add_f32_e32 v26, 1.0, v28
	v_mul_f32_e32 v28, 0xbfb8aa3b, v22
	v_add_f32_e32 v27, 1.0, v29
	v_mul_f32_e32 v29, 0xbfb8aa3b, v23
	v_exp_f32_e32 v28, v28
	v_exp_f32_e32 v29, v29
	v_rcp_f32_e32 v26, v26
	v_rcp_f32_e32 v27, v27
	v_add_f32_e32 v28, 1.0, v28
	v_add_f32_e32 v29, 1.0, v29
	v_rcp_f32_e32 v28, v28
	v_rcp_f32_e32 v29, v29
	v_pk_mul_f32 v[20:21], v[20:21], v[26:27]
	global_store_dwordx2 v[100:101], v[88:89], off
	v_pk_mul_f32 v[16:17], v[20:21], v[16:17]
	v_pk_mul_f32 v[20:21], v[22:23], v[28:29]
	v_cvt_pk_bf16_f32 v16, v16, v17
	v_pk_mul_f32 v[18:19], v[20:21], v[18:19]
	v_add_u32_e32 v20, 0xb0, v147
	v_cvt_pk_bf16_f32 v17, v18, v19
	global_store_dwordx2 v[36:37], v[16:17], off offset:32
	v_mul_f32_e32 v16, 0xbfb8aa3b, v12
	v_mul_f32_e32 v17, 0xbfb8aa3b, v13
	v_exp_f32_e32 v16, v16
	v_exp_f32_e32 v17, v17
	v_mul_f32_e32 v18, 0xbfb8aa3b, v14
	v_mul_f32_e32 v19, 0xbfb8aa3b, v15
	v_exp_f32_e32 v18, v18
	v_exp_f32_e32 v19, v19
	v_add_f32_e32 v16, 1.0, v16
	v_add_f32_e32 v17, 1.0, v17
	v_rcp_f32_e32 v16, v16
	v_rcp_f32_e32 v17, v17
	v_add_f32_e32 v18, 1.0, v18
	v_add_f32_e32 v19, 1.0, v19
	v_rcp_f32_e32 v18, v18
	v_rcp_f32_e32 v19, v19
	v_pk_mul_f32 v[12:13], v[12:13], v[16:17]
	v_mad_i64_i32 v[20:21], s[12:13], v20, s37, v[140:141]
	v_pk_mul_f32 v[8:9], v[12:13], v[8:9]
	v_pk_mul_f32 v[12:13], v[14:15], v[18:19]
	v_cvt_pk_bf16_f32 v8, v8, v9
	v_mul_f32_e32 v9, 0xbfb8aa3b, v4
	v_pk_mul_f32 v[10:11], v[12:13], v[10:11]
	v_exp_f32_e32 v12, v9
	v_mul_f32_e32 v9, 0xbfb8aa3b, v5
	v_exp_f32_e32 v13, v9
	v_cvt_pk_bf16_f32 v9, v10, v11
	v_add_f32_e32 v10, 1.0, v12
	v_mul_f32_e32 v12, 0xbfb8aa3b, v6
	v_add_f32_e32 v11, 1.0, v13
	v_mul_f32_e32 v13, 0xbfb8aa3b, v7
	v_exp_f32_e32 v12, v12
	v_exp_f32_e32 v13, v13
	v_rcp_f32_e32 v10, v10
	v_rcp_f32_e32 v11, v11
	v_add_f32_e32 v12, 1.0, v12
	v_add_f32_e32 v13, 1.0, v13
	v_rcp_f32_e32 v12, v12
	v_rcp_f32_e32 v13, v13
	v_pk_mul_f32 v[4:5], v[4:5], v[10:11]
	s_mov_b64 s[12:13], s[8:9]
	v_pk_mul_f32 v[0:1], v[4:5], v[0:1]
	v_pk_mul_f32 v[4:5], v[6:7], v[12:13]
	v_cvt_pk_bf16_f32 v0, v0, v1
	v_pk_mul_f32 v[2:3], v[4:5], v[2:3]
	global_store_dwordx2 v[84:85], v[72:73], off
	v_cvt_pk_bf16_f32 v1, v2, v3
	global_store_dwordx2 v[68:69], v[56:57], off
	global_store_dwordx2 v[52:53], v[40:41], off
	global_store_dwordx2 v[36:37], v[24:25], off
	global_store_dwordx2 v[20:21], v[8:9], off
	global_store_dwordx2 v[20:21], v[0:1], off offset:32
	s_cbranch_vccz .LBB0_3043
	s_waitcnt vmcnt(0)
	s_cmpk_gt_u32 s2, 0xff
	s_cbranch_scc1 .LBB0_3050
	s_barrier
